# nt hints also on the in-projection (QG/KV) and FFN gate/up (HM) epilogue stores: outputs consumed only after a grid barrier, keep L2 for the GEMM tiles
# baseline (speedup 1.0000x reference)
; #define LAS __attribute__((address_space(3)))
;     __device__ __forceinline__ void operator()(const Acc& acc, const Unit& u, int wr, int wc, int fr_, int fq_) const {
;     ...
;             for (int m = 0; m < 4; ++m) { const int rt = ai * HALF + wr * 64 + m * 16 + fr;
;                 const int sp = (u.pm & 15) * BM + rt; const float pos = userow ? (float)(sp >> 6) : (float)(sp & 63);
;                 float cs[4], sn[4], ga[4], gb[4];
;                 { const float* gp = g + t0; asm volatile("" : "+v"(gp));
;                   const f32x4 g1 = *(const f32x4*)gp, g2 = *(const f32x4*)(gp + hd2);
; #pragma unroll
;                   for (int p = 0; p < 4; ++p) { ga[p] = g1[p] * osc; gb[p] = g2[p] * osc; } }
; #pragma unroll
;                 for (int p = 0; p < 4; ++p) { const float ang = pos * __builtin_amdgcn_exp2f(-(float)((t0 + p) & (nf - 1)) * (13.287712379549449f / (float)nf));
;                     cs[p] = rope ? __cosf(ang) : 1.f; sn[p] = rope ? __sinf(ang) : 0.f; }
;                 bf16_t* rowp = base + (size_t)(rowbase + rt) * ld + col0;
; #pragma unroll
;                 for (int bj = 0; bj < 2; ++bj) { const f32x4 xs = *(const LAS f32x4*)(X + (rt * 2 + bj) * 4);
;                     const float tot = h128 ? ((xs[0] + xs[1]) + (xs[2] + xs[3])) : ((wc & 2) ? (xs[2] + xs[3]) : (xs[0] + xs[1]));
;                     const float rstd = rsqrtf(tot * inv_w + EPS);
;                     const f32x4 v0 = acc[ai][bj][m][0], v1 = acc[ai][bj][m][1];
;                     float o[8]; const float e[8] = {v0[0], v0[1], v0[2], v0[3], v1[0], v1[1], v1[2], v1[3]};
; #pragma unroll
;                     for (int p = 0; p < 4; ++p) { const float x1 = e[2 * p] * rstd * ga[p], x2 = e[2 * p + 1] * rstd * gb[p];
;                         o[2 * p] = x1 * cs[p] - x2 * sn[p]; o[2 * p + 1] = x2 * cs[p] + x1 * sn[p]; }
;                     *(u32x4*)(rowp + bj * HALF) = pack8(o); }
.LBB0_308:
	s_cmp_lt_i32 s92, 64
	s_cselect_b64 s[6:7], -1, 0
	s_lshl_b32 s0, s92, 8
	s_waitcnt lgkmcnt(0)
	v_cvt_f32_ubyte0_e32 v136, s26
	v_cmp_gt_i32_e64 s[8:9], s26, v160
	s_and_b32 s87, s0, 0xf00
	s_add_i32 s0, s26, -1
	v_div_scale_f32 v137, s[26:27], v136, v136, s84
	v_rcp_f32_e32 v138, v137
	s_waitcnt vmcnt(0)
	v_mov_b32_e32 v194, v128
	v_mov_b32_e32 v195, v129
	v_mov_b32_e32 v196, v130
	v_mov_b32_e32 v197, v131
	v_mov_b32_e32 v198, v132
	v_mov_b32_e32 v199, v133
	v_mov_b32_e32 v200, v134
	v_mov_b32_e32 v201, v135
	v_mul_f32_e32 v178, s43, v128
	v_and_b32_e32 v128, s0, v160
	v_cvt_f32_u32_e32 v128, v128
	v_fma_f32 v139, -v137, v138, 1.0
	v_fmac_f32_e32 v138, v139, v138
	v_div_scale_f32 v139, vcc, s84, v136, s84
	v_mul_f32_e32 v155, v139, v138
	v_fma_f32 v156, -v137, v155, v139
	v_fmac_f32_e32 v155, v156, v138
	v_fma_f32 v137, -v137, v155, v139
	v_div_fmas_f32 v137, v137, v138, v155
	v_div_fixup_f32 v185, v137, v136, s84
	v_add_u32_e32 v136, s87, v171
	v_ashrrev_i32_e32 v136, 6, v136
	v_ashrrev_i32_e32 v155, 31, v154
	v_cvt_f32_i32_e32 v136, v136
	v_mul_f32_e64 v128, v185, -v128
	v_lshl_add_u64 v[156:157], v[154:155], 1, s[88:89]
	v_exp_f32_e32 v155, v128
	v_and_b32_e32 v174, 63, v170
	v_cvt_f32_ubyte0_e32 v173, v174
	v_cndmask_b32_e64 v186, v173, v136, s[8:9]
	v_mul_f32_e32 v128, v186, v155
	v_mul_f32_e32 v128, 0.15915494, v128
	v_mul_f32_e32 v176, s43, v129
	v_cos_f32_e32 v129, v128
	v_sin_f32_e32 v128, v128
	v_mul_f32_e32 v137, s43, v134
	v_mul_f32_e32 v134, s43, v135
	v_cndmask_b32_e64 v135, 1.0, v129, s[6:7]
	v_cndmask_b32_e64 v180, 0, v128, s[6:7]
	v_bitop3_b32 v128, s0, v160, 1 bitop3:0xe0
	v_cvt_f32_u32_e32 v128, v128
	v_mul_f32_e32 v177, s43, v132
	v_mul_f32_e32 v139, s43, v133
	v_mul_f32_e32 v138, s43, v130
	v_mul_f32_e64 v128, v185, -v128
	v_exp_f32_e32 v161, v128
	v_mul_f32_e32 v136, s43, v131
	v_mul_f32_e32 v128, v186, v161
	v_mul_f32_e32 v128, 0.15915494, v128
	v_cos_f32_e32 v129, v128
	v_sin_f32_e32 v128, v128
	v_cndmask_b32_e64 v181, 1.0, v129, s[6:7]
	v_cndmask_b32_e64 v182, 0, v128, s[6:7]
	v_bitop3_b32 v128, s0, v160, 2 bitop3:0xe0
	v_cvt_f32_u32_e32 v128, v128
	v_mul_f32_e64 v128, v185, -v128
	v_exp_f32_e32 v172, v128
	s_nop 0
	v_mul_f32_e32 v128, v186, v172
	v_mul_f32_e32 v128, 0.15915494, v128
	v_cos_f32_e32 v129, v128
	v_sin_f32_e32 v128, v128
	v_cndmask_b32_e64 v183, 1.0, v129, s[6:7]
	v_cndmask_b32_e64 v184, 0, v128, s[6:7]
	v_bitop3_b32 v128, s0, v160, 3 bitop3:0xe0
	v_cvt_f32_u32_e32 v128, v128
	v_mul_f32_e64 v128, v185, -v128
	v_exp_f32_e32 v160, v128
	s_nop 0
	v_mul_f32_e32 v128, v186, v160
	v_mul_f32_e32 v128, 0.15915494, v128
	v_cos_f32_e32 v129, v128
	v_sin_f32_e32 v128, v128
	v_cndmask_b32_e64 v185, 1.0, v129, s[6:7]
	v_cndmask_b32_e64 v186, 0, v128, s[6:7]
	v_add_u32_e32 v128, s35, v171
	v_mad_i64_i32 v[128:129], s[0:1], s86, v128, 0
	v_lshl_add_u64 v[132:133], v[128:129], 1, v[156:157]
	v_fma_f32 v128, s45, v179, v168
	v_cmp_gt_f32_e32 vcc, s85, v128
	v_mul_f32_e32 v129, 0x4b800000, v128
	s_mov_b64 s[0:1], -1
	v_cndmask_b32_e32 v128, v128, v129, vcc
	v_rsq_f32_e32 v128, v128
	s_nop 0
	v_mul_f32_e32 v129, 0x45800000, v128
	v_cndmask_b32_e32 v128, v128, v129, vcc
	v_mul_f32_e32 v130, v125, v128
	v_mul_f32_e32 v129, v124, v128
	v_mul_f32_e32 v130, v177, v130
	v_mul_f32_e32 v129, v178, v129
	v_mul_f32_e32 v131, v180, v130
	v_mul_f32_e32 v130, v135, v130
	v_mul_f32_e32 v179, v127, v128
	v_fma_f32 v131, v135, v129, -v131
	v_fmac_f32_e32 v130, v180, v129
	v_mul_f32_e32 v129, v126, v128
	v_mul_f32_e32 v179, v139, v179
	v_mul_f32_e32 v129, v176, v129
	v_mul_f32_e32 v187, v182, v179
	v_mul_f32_e32 v179, v181, v179
	v_mul_f32_e32 v188, v121, v128
	v_fma_f32 v187, v181, v129, -v187
	v_fmac_f32_e32 v179, v182, v129
	v_mul_f32_e32 v129, v120, v128
	v_mul_f32_e32 v188, v137, v188
	v_mul_f32_e32 v129, v138, v129
	v_mul_f32_e32 v189, v184, v188
	v_mul_f32_e32 v188, v183, v188
	v_fma_f32 v189, v183, v129, -v189
	v_fmac_f32_e32 v188, v184, v129
	v_mul_f32_e32 v129, v122, v128
	v_mul_f32_e32 v128, v123, v128
	v_mul_f32_e32 v128, v134, v128
	v_mul_f32_e32 v129, v136, v129
	v_mul_f32_e32 v190, v186, v128
	v_mul_f32_e32 v191, v185, v128
	v_fma_f32 v190, v185, v129, -v190
	v_fmac_f32_e32 v191, v186, v129
	v_cvt_pk_bf16_f32 v128, v131, v130
	v_cvt_pk_bf16_f32 v129, v187, v179
	v_cvt_pk_bf16_f32 v130, v189, v188
	v_cvt_pk_bf16_f32 v131, v190, v191
	global_store_dwordx4 v[132:133], v[128:131], off nt
	ds_read_b128 v[128:131], v175 offset:16
	s_and_b64 vcc, exec, s[2:3]
	s_cbranch_vccnz .LBB0_314
	s_and_b64 vcc, exec, s[4:5]
	s_cbranch_vccnz .LBB0_311
	s_waitcnt lgkmcnt(0)
	v_add_f32_e32 v175, v130, v131
	s_mov_b64 s[0:1], 0

; #define LAS __attribute__((address_space(3)))
;     __device__ __forceinline__ void operator()(const Acc& acc, const Unit& u, int wr, int wc, int fr_, int fq_) const {
;     ...
;             for (int m = 0; m < 4; ++m) { const int rt = ai * HALF + wr * 64 + m * 16 + fr;
;                 const int sp = (u.pm & 15) * BM + rt; const float pos = userow ? (float)(sp >> 6) : (float)(sp & 63);
;                 float cs[4], sn[4], ga[4], gb[4];
;                 { const float* gp = g + t0; asm volatile("" : "+v"(gp));
;                   const f32x4 g1 = *(const f32x4*)gp, g2 = *(const f32x4*)(gp + hd2);
; #pragma unroll
;                   for (int p = 0; p < 4; ++p) { ga[p] = g1[p] * osc; gb[p] = g2[p] * osc; } }
;     ...
;                 for (int bj = 0; bj < 2; ++bj) { const f32x4 xs = *(const LAS f32x4*)(X + (rt * 2 + bj) * 4);
;                     const float tot = h128 ? ((xs[0] + xs[1]) + (xs[2] + xs[3])) : ((wc & 2) ? (xs[2] + xs[3]) : (xs[0] + xs[1]));
;                     const float rstd = rsqrtf(tot * inv_w + EPS);
;                     const f32x4 v0 = acc[ai][bj][m][0], v1 = acc[ai][bj][m][1];
;                     float o[8]; const float e[8] = {v0[0], v0[1], v0[2], v0[3], v1[0], v1[1], v1[2], v1[3]};
; #pragma unroll
;                     for (int p = 0; p < 4; ++p) { const float x1 = e[2 * p] * rstd * ga[p], x2 = e[2 * p + 1] * rstd * gb[p];
;                         o[2 * p] = x1 * cs[p] - x2 * sn[p]; o[2 * p + 1] = x2 * cs[p] + x1 * sn[p]; }
;                     *(u32x4*)(rowp + bj * HALF) = pack8(o); }
.LBB0_316:
	s_waitcnt lgkmcnt(0)
	v_fma_f32 v128, s45, v175, v168
	v_cmp_gt_f32_e32 vcc, s85, v128
	v_mul_f32_e32 v129, 0x4b800000, v128
	s_nop 0
	v_cndmask_b32_e32 v128, v128, v129, vcc
	v_rsq_f32_e32 v128, v128
	s_nop 0
	v_mul_f32_e32 v129, 0x45800000, v128
	v_cndmask_b32_e32 v128, v128, v129, vcc
	v_mul_f32_e32 v130, v117, v128
	v_mul_f32_e32 v129, v116, v128
	v_mul_f32_e32 v130, v177, v130
	v_mul_f32_e32 v129, v178, v129
	v_mul_f32_e32 v131, v180, v130
	v_fma_f32 v131, v135, v129, -v131
	v_mul_f32_e32 v130, v135, v130
	v_mul_f32_e32 v135, v119, v128
	v_fmac_f32_e32 v130, v180, v129
	v_mul_f32_e32 v129, v118, v128
	v_mul_f32_e32 v135, v139, v135
	v_mul_f32_e32 v129, v176, v129
	v_mul_f32_e32 v139, v182, v135
	v_mul_f32_e32 v135, v181, v135
	v_fma_f32 v139, v181, v129, -v139
	v_fmac_f32_e32 v135, v182, v129
	v_mul_f32_e32 v129, v112, v128
	v_mul_f32_e32 v129, v138, v129
	v_mul_f32_e32 v138, v113, v128
	v_mul_f32_e32 v137, v137, v138
	v_mul_f32_e32 v138, v184, v137
	v_mul_f32_e32 v137, v183, v137
	v_fma_f32 v138, v183, v129, -v138
	v_fmac_f32_e32 v137, v184, v129
	v_mul_f32_e32 v129, v114, v128
	v_mul_f32_e32 v128, v115, v128
	v_mul_f32_e32 v128, v134, v128
	v_mul_f32_e32 v129, v136, v129
	v_mul_f32_e32 v134, v186, v128
	v_mul_f32_e32 v136, v185, v128
	v_fma_f32 v134, v185, v129, -v134
	v_fmac_f32_e32 v136, v186, v129
	v_cvt_pk_bf16_f32 v128, v131, v130
	v_cvt_pk_bf16_f32 v129, v139, v135
	v_cvt_pk_bf16_f32 v130, v138, v137
	v_cvt_pk_bf16_f32 v131, v134, v136
	global_store_dwordx4 v[132:133], v[128:131], off offset:256 nt
	s_nop 1
	v_mov_b64_e32 v[128:129], v[158:159]
	v_add_u32_e32 v187, 16, v171
	v_lshl_add_u64 v[132:133], v[128:129], 0, s[22:23]
	v_mov_b32_e32 v128, v194
	v_mov_b32_e32 v129, v195
	v_mov_b32_e32 v130, v196
	v_mov_b32_e32 v131, v197
	v_mov_b32_e32 v132, v198
	v_mov_b32_e32 v133, v199
	v_mov_b32_e32 v134, v200
	v_mov_b32_e32 v135, v201
	v_lshlrev_b32_e32 v181, 5, v187
	v_add_u32_e32 v136, 0, v181
	v_add_u32_e32 v136, 0x20000, v136
	ds_read_b128 v[136:139], v136
	s_and_b64 vcc, exec, s[2:3]
	s_mov_b64 s[0:1], -1
	s_cbranch_vccnz .LBB0_322
	s_and_b64 vcc, exec, s[4:5]
	s_cbranch_vccnz .LBB0_319
	s_waitcnt lgkmcnt(0)
	v_add_f32_e32 v188, v138, v139
	s_mov_b64 s[0:1], 0

; #define LAS __attribute__((address_space(3)))
;     __device__ __forceinline__ void operator()(const Acc& acc, const Unit& u, int wr, int wc, int fr_, int fq_) const {
;     ...
;             for (int m = 0; m < 4; ++m) { const int rt = ai * HALF + wr * 64 + m * 16 + fr;
;                 const int sp = (u.pm & 15) * BM + rt; const float pos = userow ? (float)(sp >> 6) : (float)(sp & 63);
;                 float cs[4], sn[4], ga[4], gb[4];
;                 { const float* gp = g + t0; asm volatile("" : "+v"(gp));
;                   const f32x4 g1 = *(const f32x4*)gp, g2 = *(const f32x4*)(gp + hd2);
; #pragma unroll
;                   for (int p = 0; p < 4; ++p) { ga[p] = g1[p] * osc; gb[p] = g2[p] * osc; } }
; #pragma unroll
;                 for (int p = 0; p < 4; ++p) { const float ang = pos * __builtin_amdgcn_exp2f(-(float)((t0 + p) & (nf - 1)) * (13.287712379549449f / (float)nf));
;                     cs[p] = rope ? __cosf(ang) : 1.f; sn[p] = rope ? __sinf(ang) : 0.f; }
;                 bf16_t* rowp = base + (size_t)(rowbase + rt) * ld + col0;
; #pragma unroll
;                 for (int bj = 0; bj < 2; ++bj) { const f32x4 xs = *(const LAS f32x4*)(X + (rt * 2 + bj) * 4);
;                     const float tot = h128 ? ((xs[0] + xs[1]) + (xs[2] + xs[3])) : ((wc & 2) ? (xs[2] + xs[3]) : (xs[0] + xs[1]));
;                     const float rstd = rsqrtf(tot * inv_w + EPS);
;                     const f32x4 v0 = acc[ai][bj][m][0], v1 = acc[ai][bj][m][1];
;                     float o[8]; const float e[8] = {v0[0], v0[1], v0[2], v0[3], v1[0], v1[1], v1[2], v1[3]};
; #pragma unroll
;                     for (int p = 0; p < 4; ++p) { const float x1 = e[2 * p] * rstd * ga[p], x2 = e[2 * p + 1] * rstd * gb[p];
;                         o[2 * p] = x1 * cs[p] - x2 * sn[p]; o[2 * p + 1] = x2 * cs[p] + x1 * sn[p]; }
;                     *(u32x4*)(rowp + bj * HALF) = pack8(o); }
.LBB0_324:
	s_waitcnt lgkmcnt(0)
	v_add_u32_e32 v137, s87, v187
	v_ashrrev_i32_e32 v137, 6, v137
	v_cvt_f32_i32_e32 v137, v137
	v_add_u32_e32 v136, 16, v170
	v_and_b32_e32 v136, 63, v136
	v_cvt_f32_ubyte0_e32 v175, v136
	v_cndmask_b32_e64 v185, v175, v137, s[8:9]
	s_nop 0
	v_mul_f32_e32 v178, s43, v128
	v_mul_f32_e32 v128, v185, v155
	v_mul_f32_e32 v128, 0.15915494, v128
	v_mul_f32_e32 v176, s43, v129
	v_cos_f32_e32 v129, v128
	v_sin_f32_e32 v128, v128
	v_mul_f32_e32 v137, s43, v134
	v_mul_f32_e32 v134, s43, v135
	v_cndmask_b32_e64 v135, 1.0, v129, s[6:7]
	v_cndmask_b32_e64 v179, 0, v128, s[6:7]
	v_mul_f32_e32 v128, v185, v161
	v_mul_f32_e32 v128, 0.15915494, v128
	v_cos_f32_e32 v129, v128
	v_sin_f32_e32 v128, v128
	v_mul_f32_e32 v177, s43, v132
	v_mul_f32_e32 v139, s43, v133
	v_cndmask_b32_e64 v180, 1.0, v129, s[6:7]
	v_cndmask_b32_e64 v183, 0, v128, s[6:7]
	v_mul_f32_e32 v128, v185, v172
	v_mul_f32_e32 v128, 0.15915494, v128
	v_cos_f32_e32 v129, v128
	v_sin_f32_e32 v128, v128
	v_mul_f32_e32 v138, s43, v130
	v_mul_f32_e32 v136, s43, v131
	v_cndmask_b32_e64 v182, 1.0, v129, s[6:7]
	v_cndmask_b32_e64 v184, 0, v128, s[6:7]
	v_mul_f32_e32 v128, v185, v160
	v_mul_f32_e32 v128, 0.15915494, v128
	v_cos_f32_e32 v129, v128
	v_sin_f32_e32 v128, v128
	v_cndmask_b32_e64 v185, 1.0, v129, s[6:7]
	v_cndmask_b32_e64 v186, 0, v128, s[6:7]
	v_add_u32_e32 v128, s35, v187
	v_mad_i64_i32 v[128:129], s[0:1], s86, v128, 0
	v_lshl_add_u64 v[132:133], v[128:129], 1, v[156:157]
	v_fma_f32 v128, s45, v188, v168
	v_cmp_gt_f32_e32 vcc, s85, v128
	v_mul_f32_e32 v129, 0x4b800000, v128
	s_mov_b64 s[0:1], -1
	v_cndmask_b32_e32 v128, v128, v129, vcc
	v_rsq_f32_e32 v128, v128
	s_nop 0
	v_mul_f32_e32 v129, 0x45800000, v128
	v_cndmask_b32_e32 v128, v128, v129, vcc
	v_mul_f32_e32 v130, v109, v128
	v_mul_f32_e32 v129, v108, v128
	v_mul_f32_e32 v130, v177, v130
	v_mul_f32_e32 v129, v178, v129
	v_mul_f32_e32 v131, v179, v130
	v_mul_f32_e32 v130, v135, v130
	v_mul_f32_e32 v187, v111, v128
	v_fma_f32 v131, v135, v129, -v131
	v_fmac_f32_e32 v130, v179, v129
	v_mul_f32_e32 v129, v110, v128
	v_mul_f32_e32 v187, v139, v187
	v_mul_f32_e32 v129, v176, v129
	v_mul_f32_e32 v188, v183, v187
	v_mul_f32_e32 v187, v180, v187
	v_mul_f32_e32 v189, v105, v128
	v_fma_f32 v188, v180, v129, -v188
	v_fmac_f32_e32 v187, v183, v129
	v_mul_f32_e32 v129, v104, v128
	v_mul_f32_e32 v189, v137, v189
	v_mul_f32_e32 v129, v138, v129
	v_mul_f32_e32 v190, v184, v189
	v_mul_f32_e32 v189, v182, v189
	v_fma_f32 v190, v182, v129, -v190
	v_fmac_f32_e32 v189, v184, v129
	v_mul_f32_e32 v129, v106, v128
	v_mul_f32_e32 v128, v107, v128
	v_mul_f32_e32 v128, v134, v128
	v_mul_f32_e32 v129, v136, v129
	v_mul_f32_e32 v191, v186, v128
	v_mul_f32_e32 v192, v185, v128
	v_cvt_pk_bf16_f32 v128, v131, v130
	v_fma_f32 v191, v185, v129, -v191
	v_fmac_f32_e32 v192, v186, v129
	v_cvt_pk_bf16_f32 v129, v188, v187
	v_cvt_pk_bf16_f32 v130, v190, v189
	v_cvt_pk_bf16_f32 v131, v191, v192
	global_store_dwordx4 v[132:133], v[128:131], off nt
	s_and_b64 vcc, exec, s[2:3]
	s_nop 0
	v_add_u32_e32 v128, s95, v181
	ds_read_b128 v[128:131], v128 offset:16
	s_cbranch_vccnz .LBB0_330
	s_and_b64 vcc, exec, s[4:5]
	s_cbranch_vccnz .LBB0_327
	s_waitcnt lgkmcnt(0)
	v_add_f32_e32 v181, v130, v131
	s_mov_b64 s[0:1], 0

; #define LAS __attribute__((address_space(3)))
;     __device__ __forceinline__ void operator()(const Acc& acc, const Unit& u, int wr, int wc, int fr_, int fq_) const {
;     ...
;             for (int m = 0; m < 4; ++m) { const int rt = ai * HALF + wr * 64 + m * 16 + fr;
;                 const int sp = (u.pm & 15) * BM + rt; const float pos = userow ? (float)(sp >> 6) : (float)(sp & 63);
;                 float cs[4], sn[4], ga[4], gb[4];
;                 { const float* gp = g + t0; asm volatile("" : "+v"(gp));
;                   const f32x4 g1 = *(const f32x4*)gp, g2 = *(const f32x4*)(gp + hd2);
; #pragma unroll
;                   for (int p = 0; p < 4; ++p) { ga[p] = g1[p] * osc; gb[p] = g2[p] * osc; } }
;     ...
;                 for (int bj = 0; bj < 2; ++bj) { const f32x4 xs = *(const LAS f32x4*)(X + (rt * 2 + bj) * 4);
;                     const float tot = h128 ? ((xs[0] + xs[1]) + (xs[2] + xs[3])) : ((wc & 2) ? (xs[2] + xs[3]) : (xs[0] + xs[1]));
;                     const float rstd = rsqrtf(tot * inv_w + EPS);
;                     const f32x4 v0 = acc[ai][bj][m][0], v1 = acc[ai][bj][m][1];
;                     float o[8]; const float e[8] = {v0[0], v0[1], v0[2], v0[3], v1[0], v1[1], v1[2], v1[3]};
; #pragma unroll
;                     for (int p = 0; p < 4; ++p) { const float x1 = e[2 * p] * rstd * ga[p], x2 = e[2 * p + 1] * rstd * gb[p];
;                         o[2 * p] = x1 * cs[p] - x2 * sn[p]; o[2 * p + 1] = x2 * cs[p] + x1 * sn[p]; }
;                     *(u32x4*)(rowp + bj * HALF) = pack8(o); }
.LBB0_332:
	s_waitcnt lgkmcnt(0)
	v_fma_f32 v128, s45, v181, v168
	v_cmp_gt_f32_e32 vcc, s85, v128
	v_mul_f32_e32 v129, 0x4b800000, v128
	s_nop 0
	v_cndmask_b32_e32 v128, v128, v129, vcc
	v_rsq_f32_e32 v128, v128
	s_nop 0
	v_mul_f32_e32 v129, 0x45800000, v128
	v_cndmask_b32_e32 v128, v128, v129, vcc
	v_mul_f32_e32 v130, v101, v128
	v_mul_f32_e32 v129, v100, v128
	v_mul_f32_e32 v130, v177, v130
	v_mul_f32_e32 v129, v178, v129
	v_mul_f32_e32 v131, v179, v130
	v_fma_f32 v131, v135, v129, -v131
	v_mul_f32_e32 v130, v135, v130
	v_mul_f32_e32 v135, v103, v128
	v_fmac_f32_e32 v130, v179, v129
	v_mul_f32_e32 v129, v102, v128
	v_mul_f32_e32 v135, v139, v135
	v_mul_f32_e32 v129, v176, v129
	v_mul_f32_e32 v139, v183, v135
	v_mul_f32_e32 v135, v180, v135
	v_fma_f32 v139, v180, v129, -v139
	v_fmac_f32_e32 v135, v183, v129
	v_mul_f32_e32 v129, v96, v128
	v_mul_f32_e32 v129, v138, v129
	v_mul_f32_e32 v138, v97, v128
	v_mul_f32_e32 v137, v137, v138
	v_mul_f32_e32 v138, v184, v137
	v_mul_f32_e32 v137, v182, v137
	v_fma_f32 v138, v182, v129, -v138
	v_fmac_f32_e32 v137, v184, v129
	v_mul_f32_e32 v129, v98, v128
	v_mul_f32_e32 v128, v99, v128
	v_mul_f32_e32 v128, v134, v128
	v_mul_f32_e32 v129, v136, v129
	v_mul_f32_e32 v134, v186, v128
	v_mul_f32_e32 v136, v185, v128
	v_fma_f32 v134, v185, v129, -v134
	v_fmac_f32_e32 v136, v186, v129
	v_cvt_pk_bf16_f32 v128, v131, v130
	v_cvt_pk_bf16_f32 v129, v139, v135
	v_cvt_pk_bf16_f32 v130, v138, v137
	v_cvt_pk_bf16_f32 v131, v134, v136
	global_store_dwordx4 v[132:133], v[128:131], off offset:256 nt
	s_nop 1
	v_mov_b64_e32 v[128:129], v[158:159]
	v_add_u32_e32 v187, 32, v171
	v_lshl_add_u64 v[132:133], v[128:129], 0, s[22:23]
	v_mov_b32_e32 v128, v194
	v_mov_b32_e32 v129, v195
	v_mov_b32_e32 v130, v196
	v_mov_b32_e32 v131, v197
	v_mov_b32_e32 v132, v198
	v_mov_b32_e32 v133, v199
	v_mov_b32_e32 v134, v200
	v_mov_b32_e32 v135, v201
	v_lshlrev_b32_e32 v179, 5, v187
	v_add_u32_e32 v136, 0, v179
	v_add_u32_e32 v136, 0x20000, v136
	ds_read_b128 v[136:139], v136
	s_and_b64 vcc, exec, s[2:3]
	s_mov_b64 s[0:1], -1
	s_cbranch_vccnz .LBB0_338
	s_and_b64 vcc, exec, s[4:5]
	s_cbranch_vccnz .LBB0_335
	s_waitcnt lgkmcnt(0)
	v_add_f32_e32 v188, v138, v139
	s_mov_b64 s[0:1], 0

; #define LAS __attribute__((address_space(3)))
;     __device__ __forceinline__ void operator()(const Acc& acc, const Unit& u, int wr, int wc, int fr_, int fq_) const {
;     ...
;             for (int m = 0; m < 4; ++m) { const int rt = ai * HALF + wr * 64 + m * 16 + fr;
;                 const int sp = (u.pm & 15) * BM + rt; const float pos = userow ? (float)(sp >> 6) : (float)(sp & 63);
;                 float cs[4], sn[4], ga[4], gb[4];
;                 { const float* gp = g + t0; asm volatile("" : "+v"(gp));
;                   const f32x4 g1 = *(const f32x4*)gp, g2 = *(const f32x4*)(gp + hd2);
; #pragma unroll
;                   for (int p = 0; p < 4; ++p) { ga[p] = g1[p] * osc; gb[p] = g2[p] * osc; } }
; #pragma unroll
;                 for (int p = 0; p < 4; ++p) { const float ang = pos * __builtin_amdgcn_exp2f(-(float)((t0 + p) & (nf - 1)) * (13.287712379549449f / (float)nf));
;                     cs[p] = rope ? __cosf(ang) : 1.f; sn[p] = rope ? __sinf(ang) : 0.f; }
;                 bf16_t* rowp = base + (size_t)(rowbase + rt) * ld + col0;
; #pragma unroll
;                 for (int bj = 0; bj < 2; ++bj) { const f32x4 xs = *(const LAS f32x4*)(X + (rt * 2 + bj) * 4);
;                     const float tot = h128 ? ((xs[0] + xs[1]) + (xs[2] + xs[3])) : ((wc & 2) ? (xs[2] + xs[3]) : (xs[0] + xs[1]));
;                     const float rstd = rsqrtf(tot * inv_w + EPS);
;                     const f32x4 v0 = acc[ai][bj][m][0], v1 = acc[ai][bj][m][1];
;                     float o[8]; const float e[8] = {v0[0], v0[1], v0[2], v0[3], v1[0], v1[1], v1[2], v1[3]};
; #pragma unroll
;                     for (int p = 0; p < 4; ++p) { const float x1 = e[2 * p] * rstd * ga[p], x2 = e[2 * p + 1] * rstd * gb[p];
;                         o[2 * p] = x1 * cs[p] - x2 * sn[p]; o[2 * p + 1] = x2 * cs[p] + x1 * sn[p]; }
;                     *(u32x4*)(rowp + bj * HALF) = pack8(o); }
.LBB0_340:
	s_waitcnt lgkmcnt(0)
	v_add_u32_e32 v137, s87, v187
	v_ashrrev_i32_e32 v137, 6, v137
	v_cvt_f32_i32_e32 v137, v137
	v_xor_b32_e32 v136, 32, v174
	v_cvt_f32_ubyte0_e32 v174, v136
	s_nop 0
	v_mul_f32_e32 v178, s43, v128
	v_cndmask_b32_e64 v185, v174, v137, s[8:9]
	v_mul_f32_e32 v128, v185, v155
	v_mul_f32_e32 v128, 0.15915494, v128
	v_mul_f32_e32 v176, s43, v129
	v_cos_f32_e32 v129, v128
	v_sin_f32_e32 v128, v128
	v_mul_f32_e32 v137, s43, v134
	v_mul_f32_e32 v134, s43, v135
	v_cndmask_b32_e64 v135, 1.0, v129, s[6:7]
	v_cndmask_b32_e64 v180, 0, v128, s[6:7]
	v_mul_f32_e32 v128, v185, v161
	v_mul_f32_e32 v128, 0.15915494, v128
	v_cos_f32_e32 v129, v128
	v_sin_f32_e32 v128, v128
	v_mul_f32_e32 v177, s43, v132
	v_mul_f32_e32 v139, s43, v133
	v_cndmask_b32_e64 v181, 1.0, v129, s[6:7]
	v_cndmask_b32_e64 v183, 0, v128, s[6:7]
	v_mul_f32_e32 v128, v185, v172
	v_mul_f32_e32 v128, 0.15915494, v128
	v_cos_f32_e32 v129, v128
	v_sin_f32_e32 v128, v128
	v_mul_f32_e32 v138, s43, v130
	v_mul_f32_e32 v136, s43, v131
	v_cndmask_b32_e64 v182, 1.0, v129, s[6:7]
	v_cndmask_b32_e64 v184, 0, v128, s[6:7]
	v_mul_f32_e32 v128, v185, v160
	v_mul_f32_e32 v128, 0.15915494, v128
	v_cos_f32_e32 v129, v128
	v_sin_f32_e32 v128, v128
	v_cndmask_b32_e64 v185, 1.0, v129, s[6:7]
	v_cndmask_b32_e64 v186, 0, v128, s[6:7]
	v_add_u32_e32 v128, s35, v187
	v_mad_i64_i32 v[128:129], s[0:1], s86, v128, 0
	v_lshl_add_u64 v[132:133], v[128:129], 1, v[156:157]
	v_fma_f32 v128, s45, v188, v168
	v_cmp_gt_f32_e32 vcc, s85, v128
	v_mul_f32_e32 v129, 0x4b800000, v128
	s_mov_b64 s[0:1], -1
	v_cndmask_b32_e32 v128, v128, v129, vcc
	v_rsq_f32_e32 v128, v128
	s_nop 0
	v_mul_f32_e32 v129, 0x45800000, v128
	v_cndmask_b32_e32 v128, v128, v129, vcc
	v_mul_f32_e32 v130, v93, v128
	v_mul_f32_e32 v129, v92, v128
	v_mul_f32_e32 v130, v177, v130
	v_mul_f32_e32 v129, v178, v129
	v_mul_f32_e32 v131, v180, v130
	v_mul_f32_e32 v130, v135, v130
	v_mul_f32_e32 v187, v95, v128
	v_fma_f32 v131, v135, v129, -v131
	v_fmac_f32_e32 v130, v180, v129
	v_mul_f32_e32 v129, v94, v128
	v_mul_f32_e32 v187, v139, v187
	v_mul_f32_e32 v129, v176, v129
	v_mul_f32_e32 v188, v183, v187
	v_mul_f32_e32 v187, v181, v187
	v_mul_f32_e32 v189, v89, v128
	v_fma_f32 v188, v181, v129, -v188
	v_fmac_f32_e32 v187, v183, v129
	v_mul_f32_e32 v129, v88, v128
	v_mul_f32_e32 v189, v137, v189
	v_mul_f32_e32 v129, v138, v129
	v_mul_f32_e32 v190, v184, v189
	v_mul_f32_e32 v189, v182, v189
	v_fma_f32 v190, v182, v129, -v190
	v_fmac_f32_e32 v189, v184, v129
	v_mul_f32_e32 v129, v90, v128
	v_mul_f32_e32 v128, v91, v128
	v_mul_f32_e32 v128, v134, v128
	v_mul_f32_e32 v129, v136, v129
	v_mul_f32_e32 v191, v186, v128
	v_mul_f32_e32 v192, v185, v128
	v_cvt_pk_bf16_f32 v128, v131, v130
	v_fma_f32 v191, v185, v129, -v191
	v_fmac_f32_e32 v192, v186, v129
	v_cvt_pk_bf16_f32 v129, v188, v187
	v_cvt_pk_bf16_f32 v130, v190, v189
	v_cvt_pk_bf16_f32 v131, v191, v192
	global_store_dwordx4 v[132:133], v[128:131], off nt
	s_and_b64 vcc, exec, s[2:3]
	s_nop 0
	v_add_u32_e32 v128, s95, v179
	ds_read_b128 v[128:131], v128 offset:16
	s_cbranch_vccnz .LBB0_346
	s_and_b64 vcc, exec, s[4:5]
	s_cbranch_vccnz .LBB0_343
	s_waitcnt lgkmcnt(0)
	v_add_f32_e32 v179, v130, v131
	s_mov_b64 s[0:1], 0

; #define LAS __attribute__((address_space(3)))
;     __device__ __forceinline__ void operator()(const Acc& acc, const Unit& u, int wr, int wc, int fr_, int fq_) const {
;     ...
;             for (int m = 0; m < 4; ++m) { const int rt = ai * HALF + wr * 64 + m * 16 + fr;
;                 const int sp = (u.pm & 15) * BM + rt; const float pos = userow ? (float)(sp >> 6) : (float)(sp & 63);
;                 float cs[4], sn[4], ga[4], gb[4];
;                 { const float* gp = g + t0; asm volatile("" : "+v"(gp));
;                   const f32x4 g1 = *(const f32x4*)gp, g2 = *(const f32x4*)(gp + hd2);
; #pragma unroll
;                   for (int p = 0; p < 4; ++p) { ga[p] = g1[p] * osc; gb[p] = g2[p] * osc; } }
;     ...
;                 for (int bj = 0; bj < 2; ++bj) { const f32x4 xs = *(const LAS f32x4*)(X + (rt * 2 + bj) * 4);
;                     const float tot = h128 ? ((xs[0] + xs[1]) + (xs[2] + xs[3])) : ((wc & 2) ? (xs[2] + xs[3]) : (xs[0] + xs[1]));
;                     const float rstd = rsqrtf(tot * inv_w + EPS);
;                     const f32x4 v0 = acc[ai][bj][m][0], v1 = acc[ai][bj][m][1];
;                     float o[8]; const float e[8] = {v0[0], v0[1], v0[2], v0[3], v1[0], v1[1], v1[2], v1[3]};
; #pragma unroll
;                     for (int p = 0; p < 4; ++p) { const float x1 = e[2 * p] * rstd * ga[p], x2 = e[2 * p + 1] * rstd * gb[p];
;                         o[2 * p] = x1 * cs[p] - x2 * sn[p]; o[2 * p + 1] = x2 * cs[p] + x1 * sn[p]; }
;                     *(u32x4*)(rowp + bj * HALF) = pack8(o); }
.LBB0_348:
	s_waitcnt lgkmcnt(0)
	v_fma_f32 v128, s45, v179, v168
	v_cmp_gt_f32_e32 vcc, s85, v128
	v_mul_f32_e32 v129, 0x4b800000, v128
	s_nop 0
	v_cndmask_b32_e32 v128, v128, v129, vcc
	v_rsq_f32_e32 v128, v128
	s_nop 0
	v_mul_f32_e32 v129, 0x45800000, v128
	v_cndmask_b32_e32 v128, v128, v129, vcc
	v_mul_f32_e32 v130, v85, v128
	v_mul_f32_e32 v129, v84, v128
	v_mul_f32_e32 v130, v177, v130
	v_mul_f32_e32 v129, v178, v129
	v_mul_f32_e32 v131, v180, v130
	v_fma_f32 v131, v135, v129, -v131
	v_mul_f32_e32 v130, v135, v130
	v_mul_f32_e32 v135, v87, v128
	v_fmac_f32_e32 v130, v180, v129
	v_mul_f32_e32 v129, v86, v128
	v_mul_f32_e32 v135, v139, v135
	v_mul_f32_e32 v129, v176, v129
	v_mul_f32_e32 v139, v183, v135
	v_mul_f32_e32 v135, v181, v135
	v_fma_f32 v139, v181, v129, -v139
	v_fmac_f32_e32 v135, v183, v129
	v_mul_f32_e32 v129, v80, v128
	v_mul_f32_e32 v129, v138, v129
	v_mul_f32_e32 v138, v81, v128
	v_mul_f32_e32 v137, v137, v138
	v_mul_f32_e32 v138, v184, v137
	v_mul_f32_e32 v137, v182, v137
	v_fma_f32 v138, v182, v129, -v138
	v_fmac_f32_e32 v137, v184, v129
	v_mul_f32_e32 v129, v82, v128
	v_mul_f32_e32 v128, v83, v128
	v_mul_f32_e32 v128, v134, v128
	v_mul_f32_e32 v129, v136, v129
	v_mul_f32_e32 v134, v186, v128
	v_mul_f32_e32 v136, v185, v128
	v_fma_f32 v134, v185, v129, -v134
	v_fmac_f32_e32 v136, v186, v129
	v_cvt_pk_bf16_f32 v128, v131, v130
	v_cvt_pk_bf16_f32 v129, v139, v135
	v_cvt_pk_bf16_f32 v130, v138, v137
	v_cvt_pk_bf16_f32 v131, v134, v136
	global_store_dwordx4 v[132:133], v[128:131], off offset:256 nt
	s_nop 1
	v_mov_b64_e32 v[128:129], v[158:159]
	v_add_u32_e32 v188, 48, v171
	v_lshl_add_u64 v[132:133], v[128:129], 0, s[22:23]
	v_mov_b32_e32 v128, v194
	v_mov_b32_e32 v129, v195
	v_mov_b32_e32 v130, v196
	v_mov_b32_e32 v131, v197
	v_mov_b32_e32 v132, v198
	v_mov_b32_e32 v133, v199
	v_mov_b32_e32 v134, v200
	v_mov_b32_e32 v135, v201
	v_lshlrev_b32_e32 v182, 5, v188
	v_add_u32_e32 v136, 0, v182
	v_add_u32_e32 v136, 0x20000, v136
	ds_read_b128 v[136:139], v136
	s_and_b64 vcc, exec, s[2:3]
	s_mov_b64 s[0:1], -1
	s_cbranch_vccnz .LBB0_354
	s_and_b64 vcc, exec, s[4:5]
	s_cbranch_vccnz .LBB0_351
	s_waitcnt lgkmcnt(0)
	v_add_f32_e32 v189, v138, v139
	s_mov_b64 s[0:1], 0

; #define LAS __attribute__((address_space(3)))
;     __device__ __forceinline__ void operator()(const Acc& acc, const Unit& u, int wr, int wc, int fr_, int fq_) const {
;     ...
;             for (int m = 0; m < 4; ++m) { const int rt = ai * HALF + wr * 64 + m * 16 + fr;
;                 const int sp = (u.pm & 15) * BM + rt; const float pos = userow ? (float)(sp >> 6) : (float)(sp & 63);
;                 float cs[4], sn[4], ga[4], gb[4];
;                 { const float* gp = g + t0; asm volatile("" : "+v"(gp));
;                   const f32x4 g1 = *(const f32x4*)gp, g2 = *(const f32x4*)(gp + hd2);
; #pragma unroll
;                   for (int p = 0; p < 4; ++p) { ga[p] = g1[p] * osc; gb[p] = g2[p] * osc; } }
; #pragma unroll
;                 for (int p = 0; p < 4; ++p) { const float ang = pos * __builtin_amdgcn_exp2f(-(float)((t0 + p) & (nf - 1)) * (13.287712379549449f / (float)nf));
;                     cs[p] = rope ? __cosf(ang) : 1.f; sn[p] = rope ? __sinf(ang) : 0.f; }
;                 bf16_t* rowp = base + (size_t)(rowbase + rt) * ld + col0;
; #pragma unroll
;                 for (int bj = 0; bj < 2; ++bj) { const f32x4 xs = *(const LAS f32x4*)(X + (rt * 2 + bj) * 4);
;                     const float tot = h128 ? ((xs[0] + xs[1]) + (xs[2] + xs[3])) : ((wc & 2) ? (xs[2] + xs[3]) : (xs[0] + xs[1]));
;                     const float rstd = rsqrtf(tot * inv_w + EPS);
;                     const f32x4 v0 = acc[ai][bj][m][0], v1 = acc[ai][bj][m][1];
;                     float o[8]; const float e[8] = {v0[0], v0[1], v0[2], v0[3], v1[0], v1[1], v1[2], v1[3]};
; #pragma unroll
;                     for (int p = 0; p < 4; ++p) { const float x1 = e[2 * p] * rstd * ga[p], x2 = e[2 * p + 1] * rstd * gb[p];
;                         o[2 * p] = x1 * cs[p] - x2 * sn[p]; o[2 * p + 1] = x2 * cs[p] + x1 * sn[p]; }
;                     *(u32x4*)(rowp + bj * HALF) = pack8(o); }
.LBB0_356:
	s_waitcnt lgkmcnt(0)
	v_add_u32_e32 v137, s87, v188
	v_ashrrev_i32_e32 v137, 6, v137
	v_cvt_f32_i32_e32 v137, v137
	v_add_u32_e32 v136, 48, v170
	v_and_b32_e32 v136, 63, v136
	v_cvt_f32_ubyte0_e32 v176, v136
	v_cndmask_b32_e64 v186, v176, v137, s[8:9]
	s_nop 0
	v_mul_f32_e32 v179, s43, v128
	v_mul_f32_e32 v128, v186, v155
	v_mul_f32_e32 v128, 0.15915494, v128
	v_mul_f32_e32 v177, s43, v129
	v_cos_f32_e32 v129, v128
	v_sin_f32_e32 v128, v128
	v_mul_f32_e32 v137, s43, v134
	v_mul_f32_e32 v134, s43, v135
	v_cndmask_b32_e64 v135, 1.0, v129, s[6:7]
	v_cndmask_b32_e64 v180, 0, v128, s[6:7]
	v_mul_f32_e32 v128, v186, v161
	v_mul_f32_e32 v128, 0.15915494, v128
	v_cos_f32_e32 v129, v128
	v_sin_f32_e32 v128, v128
	v_mul_f32_e32 v178, s43, v132
	v_mul_f32_e32 v139, s43, v133
	v_cndmask_b32_e64 v181, 1.0, v129, s[6:7]
	v_cndmask_b32_e64 v184, 0, v128, s[6:7]
	v_mul_f32_e32 v128, v186, v172
	v_mul_f32_e32 v128, 0.15915494, v128
	v_cos_f32_e32 v129, v128
	v_sin_f32_e32 v128, v128
	v_mul_f32_e32 v138, s43, v130
	v_mul_f32_e32 v136, s43, v131
	v_cndmask_b32_e64 v183, 1.0, v129, s[6:7]
	v_cndmask_b32_e64 v185, 0, v128, s[6:7]
	v_mul_f32_e32 v128, v186, v160
	v_mul_f32_e32 v128, 0.15915494, v128
	v_cos_f32_e32 v129, v128
	v_sin_f32_e32 v128, v128
	v_cndmask_b32_e64 v186, 1.0, v129, s[6:7]
	v_cndmask_b32_e64 v187, 0, v128, s[6:7]
	v_add_u32_e32 v128, s35, v188
	v_mad_i64_i32 v[128:129], s[0:1], s86, v128, 0
	v_lshl_add_u64 v[132:133], v[128:129], 1, v[156:157]
	v_fma_f32 v128, s45, v189, v168
	v_cmp_gt_f32_e32 vcc, s85, v128
	v_mul_f32_e32 v129, 0x4b800000, v128
	s_mov_b64 s[0:1], -1
	v_cndmask_b32_e32 v128, v128, v129, vcc
	v_rsq_f32_e32 v128, v128
	s_nop 0
	v_mul_f32_e32 v129, 0x45800000, v128
	v_cndmask_b32_e32 v128, v128, v129, vcc
	v_mul_f32_e32 v130, v77, v128
	v_mul_f32_e32 v129, v76, v128
	v_mul_f32_e32 v130, v178, v130
	v_mul_f32_e32 v129, v179, v129
	v_mul_f32_e32 v131, v180, v130
	v_mul_f32_e32 v130, v135, v130
	v_mul_f32_e32 v188, v79, v128
	v_fma_f32 v131, v135, v129, -v131
	v_fmac_f32_e32 v130, v180, v129
	v_mul_f32_e32 v129, v78, v128
	v_mul_f32_e32 v188, v139, v188
	v_mul_f32_e32 v129, v177, v129
	v_mul_f32_e32 v189, v184, v188
	v_mul_f32_e32 v188, v181, v188
	v_mul_f32_e32 v190, v73, v128
	v_fma_f32 v189, v181, v129, -v189
	v_fmac_f32_e32 v188, v184, v129
	v_mul_f32_e32 v129, v72, v128
	v_mul_f32_e32 v190, v137, v190
	v_mul_f32_e32 v129, v138, v129
	v_mul_f32_e32 v191, v185, v190
	v_mul_f32_e32 v190, v183, v190
	v_fma_f32 v191, v183, v129, -v191
	v_fmac_f32_e32 v190, v185, v129
	v_mul_f32_e32 v129, v74, v128
	v_mul_f32_e32 v128, v75, v128
	v_mul_f32_e32 v128, v134, v128
	v_mul_f32_e32 v129, v136, v129
	v_mul_f32_e32 v192, v187, v128
	v_mul_f32_e32 v193, v186, v128
	v_cvt_pk_bf16_f32 v128, v131, v130
	v_fma_f32 v192, v186, v129, -v192
	v_fmac_f32_e32 v193, v187, v129
	v_cvt_pk_bf16_f32 v129, v189, v188
	v_cvt_pk_bf16_f32 v130, v191, v190
	v_cvt_pk_bf16_f32 v131, v192, v193
	global_store_dwordx4 v[132:133], v[128:131], off nt
	s_and_b64 vcc, exec, s[2:3]
	s_nop 0
	v_add_u32_e32 v128, s95, v182
	ds_read_b128 v[128:131], v128 offset:16
	s_cbranch_vccnz .LBB0_362
	s_and_b64 vcc, exec, s[4:5]
	s_cbranch_vccnz .LBB0_359
	s_waitcnt lgkmcnt(0)
	v_add_f32_e32 v182, v130, v131
	s_mov_b64 s[0:1], 0

; #define LAS __attribute__((address_space(3)))
;     __device__ __forceinline__ void operator()(const Acc& acc, const Unit& u, int wr, int wc, int fr_, int fq_) const {
;     ...
;             for (int m = 0; m < 4; ++m) { const int rt = ai * HALF + wr * 64 + m * 16 + fr;
;                 const int sp = (u.pm & 15) * BM + rt; const float pos = userow ? (float)(sp >> 6) : (float)(sp & 63);
;                 float cs[4], sn[4], ga[4], gb[4];
;                 { const float* gp = g + t0; asm volatile("" : "+v"(gp));
;                   const f32x4 g1 = *(const f32x4*)gp, g2 = *(const f32x4*)(gp + hd2);
; #pragma unroll
;                   for (int p = 0; p < 4; ++p) { ga[p] = g1[p] * osc; gb[p] = g2[p] * osc; } }
;     ...
;                 for (int bj = 0; bj < 2; ++bj) { const f32x4 xs = *(const LAS f32x4*)(X + (rt * 2 + bj) * 4);
;                     const float tot = h128 ? ((xs[0] + xs[1]) + (xs[2] + xs[3])) : ((wc & 2) ? (xs[2] + xs[3]) : (xs[0] + xs[1]));
;                     const float rstd = rsqrtf(tot * inv_w + EPS);
;                     const f32x4 v0 = acc[ai][bj][m][0], v1 = acc[ai][bj][m][1];
;                     float o[8]; const float e[8] = {v0[0], v0[1], v0[2], v0[3], v1[0], v1[1], v1[2], v1[3]};
; #pragma unroll
;                     for (int p = 0; p < 4; ++p) { const float x1 = e[2 * p] * rstd * ga[p], x2 = e[2 * p + 1] * rstd * gb[p];
;                         o[2 * p] = x1 * cs[p] - x2 * sn[p]; o[2 * p + 1] = x2 * cs[p] + x1 * sn[p]; }
;                     *(u32x4*)(rowp + bj * HALF) = pack8(o); }
.LBB0_364:
	s_waitcnt lgkmcnt(0)
	v_fma_f32 v128, s45, v182, v168
	v_cmp_gt_f32_e32 vcc, s85, v128
	v_mul_f32_e32 v129, 0x4b800000, v128
	s_nop 0
	v_cndmask_b32_e32 v128, v128, v129, vcc
	v_rsq_f32_e32 v128, v128
	s_nop 0
	v_mul_f32_e32 v129, 0x45800000, v128
	v_cndmask_b32_e32 v128, v128, v129, vcc
	v_mul_f32_e32 v130, v69, v128
	v_mul_f32_e32 v129, v68, v128
	v_mul_f32_e32 v130, v178, v130
	v_mul_f32_e32 v129, v179, v129
	v_mul_f32_e32 v131, v180, v130
	v_fma_f32 v131, v135, v129, -v131
	v_mul_f32_e32 v130, v135, v130
	v_mul_f32_e32 v135, v71, v128
	v_fmac_f32_e32 v130, v180, v129
	v_mul_f32_e32 v129, v70, v128
	v_mul_f32_e32 v135, v139, v135
	v_mul_f32_e32 v129, v177, v129
	v_mul_f32_e32 v139, v184, v135
	v_mul_f32_e32 v135, v181, v135
	v_fma_f32 v139, v181, v129, -v139
	v_fmac_f32_e32 v135, v184, v129
	v_mul_f32_e32 v129, v64, v128
	v_mul_f32_e32 v129, v138, v129
	v_mul_f32_e32 v138, v65, v128
	v_mul_f32_e32 v137, v137, v138
	v_mul_f32_e32 v138, v185, v137
	v_mul_f32_e32 v137, v183, v137
	v_fma_f32 v138, v183, v129, -v138
	v_fmac_f32_e32 v137, v185, v129
	v_mul_f32_e32 v129, v66, v128
	v_mul_f32_e32 v128, v67, v128
	v_mul_f32_e32 v128, v134, v128
	v_mul_f32_e32 v129, v136, v129
	v_mul_f32_e32 v134, v187, v128
	v_mul_f32_e32 v136, v186, v128
	v_fma_f32 v134, v186, v129, -v134
	v_fmac_f32_e32 v136, v187, v129
	v_cvt_pk_bf16_f32 v128, v131, v130
	v_cvt_pk_bf16_f32 v129, v139, v135
	v_cvt_pk_bf16_f32 v130, v138, v137
	v_cvt_pk_bf16_f32 v131, v134, v136
	global_store_dwordx4 v[132:133], v[128:131], off offset:256 nt
	s_nop 1
	v_mov_b64_e32 v[128:129], v[158:159]
	v_add_u32_e32 v187, 0x80, v171
	v_lshl_add_u64 v[132:133], v[128:129], 0, s[22:23]
	v_mov_b32_e32 v128, v194
	v_mov_b32_e32 v129, v195
	v_mov_b32_e32 v130, v196
	v_mov_b32_e32 v131, v197
	v_mov_b32_e32 v132, v198
	v_mov_b32_e32 v133, v199
	v_mov_b32_e32 v134, v200
	v_mov_b32_e32 v135, v201
	v_lshlrev_b32_e32 v181, 5, v187
	v_add_u32_e32 v136, 0, v181
	v_add_u32_e32 v136, 0x20000, v136
	ds_read_b128 v[136:139], v136
	s_and_b64 vcc, exec, s[2:3]
	s_mov_b64 s[0:1], -1
	s_cbranch_vccnz .LBB0_370
	s_and_b64 vcc, exec, s[4:5]
	s_cbranch_vccnz .LBB0_367
	s_waitcnt lgkmcnt(0)
	v_add_f32_e32 v188, v138, v139
	s_mov_b64 s[0:1], 0

; #define LAS __attribute__((address_space(3)))
;     __device__ __forceinline__ void operator()(const Acc& acc, const Unit& u, int wr, int wc, int fr_, int fq_) const {
;     ...
;             for (int m = 0; m < 4; ++m) { const int rt = ai * HALF + wr * 64 + m * 16 + fr;
;                 const int sp = (u.pm & 15) * BM + rt; const float pos = userow ? (float)(sp >> 6) : (float)(sp & 63);
;                 float cs[4], sn[4], ga[4], gb[4];
;                 { const float* gp = g + t0; asm volatile("" : "+v"(gp));
;                   const f32x4 g1 = *(const f32x4*)gp, g2 = *(const f32x4*)(gp + hd2);
; #pragma unroll
;                   for (int p = 0; p < 4; ++p) { ga[p] = g1[p] * osc; gb[p] = g2[p] * osc; } }
; #pragma unroll
;                 for (int p = 0; p < 4; ++p) { const float ang = pos * __builtin_amdgcn_exp2f(-(float)((t0 + p) & (nf - 1)) * (13.287712379549449f / (float)nf));
;                     cs[p] = rope ? __cosf(ang) : 1.f; sn[p] = rope ? __sinf(ang) : 0.f; }
;                 bf16_t* rowp = base + (size_t)(rowbase + rt) * ld + col0;
; #pragma unroll
;                 for (int bj = 0; bj < 2; ++bj) { const f32x4 xs = *(const LAS f32x4*)(X + (rt * 2 + bj) * 4);
;                     const float tot = h128 ? ((xs[0] + xs[1]) + (xs[2] + xs[3])) : ((wc & 2) ? (xs[2] + xs[3]) : (xs[0] + xs[1]));
;                     const float rstd = rsqrtf(tot * inv_w + EPS);
;                     const f32x4 v0 = acc[ai][bj][m][0], v1 = acc[ai][bj][m][1];
;                     float o[8]; const float e[8] = {v0[0], v0[1], v0[2], v0[3], v1[0], v1[1], v1[2], v1[3]};
; #pragma unroll
;                     for (int p = 0; p < 4; ++p) { const float x1 = e[2 * p] * rstd * ga[p], x2 = e[2 * p + 1] * rstd * gb[p];
;                         o[2 * p] = x1 * cs[p] - x2 * sn[p]; o[2 * p + 1] = x2 * cs[p] + x1 * sn[p]; }
;                     *(u32x4*)(rowp + bj * HALF) = pack8(o); }
.LBB0_372:
	s_waitcnt lgkmcnt(0)
	v_add_u32_e32 v136, s87, v187
	v_ashrrev_i32_e32 v136, 6, v136
	v_cvt_f32_i32_e32 v136, v136
	s_nop 0
	v_mul_f32_e32 v178, s43, v128
	v_mul_f32_e32 v139, s43, v129
	v_mul_f32_e32 v137, s43, v134
	v_cndmask_b32_e64 v185, v173, v136, s[8:9]
	v_mul_f32_e32 v128, v185, v155
	v_mul_f32_e32 v128, 0.15915494, v128
	v_cos_f32_e32 v129, v128
	v_sin_f32_e32 v128, v128
	v_mul_f32_e32 v134, s43, v135
	v_mul_f32_e32 v177, s43, v132
	v_cndmask_b32_e64 v135, 1.0, v129, s[6:7]
	v_cndmask_b32_e64 v179, 0, v128, s[6:7]
	v_mul_f32_e32 v128, v185, v161
	v_mul_f32_e32 v128, 0.15915494, v128
	v_cos_f32_e32 v129, v128
	v_sin_f32_e32 v128, v128
	v_mul_f32_e32 v173, s43, v133
	v_mul_f32_e32 v138, s43, v130
	v_cndmask_b32_e64 v180, 1.0, v129, s[6:7]
	v_cndmask_b32_e64 v183, 0, v128, s[6:7]
	v_mul_f32_e32 v128, v185, v172
	v_mul_f32_e32 v128, 0.15915494, v128
	v_cos_f32_e32 v129, v128
	v_sin_f32_e32 v128, v128
	v_mul_f32_e32 v136, s43, v131
	v_cndmask_b32_e64 v182, 1.0, v129, s[6:7]
	v_cndmask_b32_e64 v184, 0, v128, s[6:7]
	v_mul_f32_e32 v128, v185, v160
	v_mul_f32_e32 v128, 0.15915494, v128
	v_cos_f32_e32 v129, v128
	v_sin_f32_e32 v128, v128
	v_cndmask_b32_e64 v185, 1.0, v129, s[6:7]
	v_cndmask_b32_e64 v186, 0, v128, s[6:7]
	v_add_u32_e32 v128, s35, v187
	v_mad_i64_i32 v[128:129], s[0:1], s86, v128, 0
	v_lshl_add_u64 v[132:133], v[128:129], 1, v[156:157]
	v_fma_f32 v128, s45, v188, v168
	v_cmp_gt_f32_e32 vcc, s85, v128
	v_mul_f32_e32 v129, 0x4b800000, v128
	s_mov_b64 s[0:1], -1
	v_cndmask_b32_e32 v128, v128, v129, vcc
	v_rsq_f32_e32 v128, v128
	s_nop 0
	v_mul_f32_e32 v129, 0x45800000, v128
	v_cndmask_b32_e32 v128, v128, v129, vcc
	v_mul_f32_e32 v130, v61, v128
	v_mul_f32_e32 v129, v60, v128
	v_mul_f32_e32 v130, v177, v130
	v_mul_f32_e32 v129, v178, v129
	v_mul_f32_e32 v131, v179, v130
	v_mul_f32_e32 v130, v135, v130
	v_mul_f32_e32 v187, v63, v128
	v_fma_f32 v131, v135, v129, -v131
	v_fmac_f32_e32 v130, v179, v129
	v_mul_f32_e32 v129, v62, v128
	v_mul_f32_e32 v187, v173, v187
	v_mul_f32_e32 v129, v139, v129
	v_mul_f32_e32 v188, v183, v187
	v_mul_f32_e32 v187, v180, v187
	v_mul_f32_e32 v189, v57, v128
	v_fma_f32 v188, v180, v129, -v188
	v_fmac_f32_e32 v187, v183, v129
	v_mul_f32_e32 v129, v56, v128
	v_mul_f32_e32 v189, v137, v189
	v_mul_f32_e32 v129, v138, v129
	v_mul_f32_e32 v190, v184, v189
	v_mul_f32_e32 v189, v182, v189
	v_fma_f32 v190, v182, v129, -v190
	v_fmac_f32_e32 v189, v184, v129
	v_mul_f32_e32 v129, v58, v128
	v_mul_f32_e32 v128, v59, v128
	v_mul_f32_e32 v128, v134, v128
	v_mul_f32_e32 v129, v136, v129
	v_mul_f32_e32 v191, v186, v128
	v_mul_f32_e32 v192, v185, v128
	v_cvt_pk_bf16_f32 v128, v131, v130
	v_fma_f32 v191, v185, v129, -v191
	v_fmac_f32_e32 v192, v186, v129
	v_cvt_pk_bf16_f32 v129, v188, v187
	v_cvt_pk_bf16_f32 v130, v190, v189
	v_cvt_pk_bf16_f32 v131, v191, v192
	global_store_dwordx4 v[132:133], v[128:131], off nt
	s_and_b64 vcc, exec, s[2:3]
	s_nop 0
	v_add_u32_e32 v128, s95, v181
	ds_read_b128 v[128:131], v128 offset:16
	s_cbranch_vccnz .LBB0_378
	s_and_b64 vcc, exec, s[4:5]
	s_cbranch_vccnz .LBB0_375
	s_waitcnt lgkmcnt(0)
	v_add_f32_e32 v181, v130, v131
	s_mov_b64 s[0:1], 0

; #define LAS __attribute__((address_space(3)))
;     __device__ __forceinline__ void operator()(const Acc& acc, const Unit& u, int wr, int wc, int fr_, int fq_) const {
;     ...
;             for (int m = 0; m < 4; ++m) { const int rt = ai * HALF + wr * 64 + m * 16 + fr;
;                 const int sp = (u.pm & 15) * BM + rt; const float pos = userow ? (float)(sp >> 6) : (float)(sp & 63);
;                 float cs[4], sn[4], ga[4], gb[4];
;                 { const float* gp = g + t0; asm volatile("" : "+v"(gp));
;                   const f32x4 g1 = *(const f32x4*)gp, g2 = *(const f32x4*)(gp + hd2);
; #pragma unroll
;                   for (int p = 0; p < 4; ++p) { ga[p] = g1[p] * osc; gb[p] = g2[p] * osc; } }
;     ...
;                 for (int bj = 0; bj < 2; ++bj) { const f32x4 xs = *(const LAS f32x4*)(X + (rt * 2 + bj) * 4);
;                     const float tot = h128 ? ((xs[0] + xs[1]) + (xs[2] + xs[3])) : ((wc & 2) ? (xs[2] + xs[3]) : (xs[0] + xs[1]));
;                     const float rstd = rsqrtf(tot * inv_w + EPS);
;                     const f32x4 v0 = acc[ai][bj][m][0], v1 = acc[ai][bj][m][1];
;                     float o[8]; const float e[8] = {v0[0], v0[1], v0[2], v0[3], v1[0], v1[1], v1[2], v1[3]};
; #pragma unroll
;                     for (int p = 0; p < 4; ++p) { const float x1 = e[2 * p] * rstd * ga[p], x2 = e[2 * p + 1] * rstd * gb[p];
;                         o[2 * p] = x1 * cs[p] - x2 * sn[p]; o[2 * p + 1] = x2 * cs[p] + x1 * sn[p]; }
;                     *(u32x4*)(rowp + bj * HALF) = pack8(o); }
.LBB0_380:
	s_waitcnt lgkmcnt(0)
	v_fma_f32 v128, s45, v181, v168
	v_cmp_gt_f32_e32 vcc, s85, v128
	v_mul_f32_e32 v129, 0x4b800000, v128
	s_nop 0
	v_cndmask_b32_e32 v128, v128, v129, vcc
	v_rsq_f32_e32 v128, v128
	s_nop 0
	v_mul_f32_e32 v129, 0x45800000, v128
	v_cndmask_b32_e32 v128, v128, v129, vcc
	v_mul_f32_e32 v130, v53, v128
	v_mul_f32_e32 v129, v52, v128
	v_mul_f32_e32 v130, v177, v130
	v_mul_f32_e32 v129, v178, v129
	v_mul_f32_e32 v131, v179, v130
	v_fma_f32 v131, v135, v129, -v131
	v_mul_f32_e32 v130, v135, v130
	v_mul_f32_e32 v135, v55, v128
	v_fmac_f32_e32 v130, v179, v129
	v_mul_f32_e32 v129, v54, v128
	v_mul_f32_e32 v135, v173, v135
	v_mul_f32_e32 v129, v139, v129
	v_mul_f32_e32 v139, v183, v135
	v_mul_f32_e32 v135, v180, v135
	v_fma_f32 v139, v180, v129, -v139
	v_fmac_f32_e32 v135, v183, v129
	v_mul_f32_e32 v129, v48, v128
	v_mul_f32_e32 v129, v138, v129
	v_mul_f32_e32 v138, v49, v128
	v_mul_f32_e32 v137, v137, v138
	v_mul_f32_e32 v138, v184, v137
	v_mul_f32_e32 v137, v182, v137
	v_fma_f32 v138, v182, v129, -v138
	v_fmac_f32_e32 v137, v184, v129
	v_mul_f32_e32 v129, v50, v128
	v_mul_f32_e32 v128, v51, v128
	v_mul_f32_e32 v128, v134, v128
	v_mul_f32_e32 v129, v136, v129
	v_mul_f32_e32 v134, v186, v128
	v_mul_f32_e32 v136, v185, v128
	v_fma_f32 v134, v185, v129, -v134
	v_fmac_f32_e32 v136, v186, v129
	v_cvt_pk_bf16_f32 v128, v131, v130
	v_cvt_pk_bf16_f32 v129, v139, v135
	v_cvt_pk_bf16_f32 v130, v138, v137
	v_cvt_pk_bf16_f32 v131, v134, v136
	global_store_dwordx4 v[132:133], v[128:131], off offset:256 nt
	s_nop 1
	v_mov_b64_e32 v[128:129], v[158:159]
	v_add_u32_e32 v186, 0x90, v171
	v_lshl_add_u64 v[132:133], v[128:129], 0, s[22:23]
	v_mov_b32_e32 v128, v194
	v_mov_b32_e32 v129, v195
	v_mov_b32_e32 v130, v196
	v_mov_b32_e32 v131, v197
	v_mov_b32_e32 v132, v198
	v_mov_b32_e32 v133, v199
	v_mov_b32_e32 v134, v200
	v_mov_b32_e32 v135, v201
	v_lshlrev_b32_e32 v180, 5, v186
	v_add_u32_e32 v136, 0, v180
	v_add_u32_e32 v136, 0x20000, v136
	ds_read_b128 v[136:139], v136
	s_and_b64 vcc, exec, s[2:3]
	s_mov_b64 s[0:1], -1
	s_cbranch_vccnz .LBB0_386
	s_and_b64 vcc, exec, s[4:5]
	s_cbranch_vccnz .LBB0_383
	s_waitcnt lgkmcnt(0)
	v_add_f32_e32 v187, v138, v139
	s_mov_b64 s[0:1], 0

; #define LAS __attribute__((address_space(3)))
; #define EPI_FENCE() asm volatile("" ::: "memory")
;     __device__ __forceinline__ void operator()(const Acc& acc, const Unit& u, int wr, int wc, int fr_, int fq_) const {
;     ...
; #pragma unroll
;         for (int ai = 0; ai < 2; ++ai)
; #pragma unroll
;             for (int m = 0; m < 4; ++m) { const int rt = ai * HALF + wr * 64 + m * 16 + fr;
;                 const int sp = (u.pm & 15) * BM + rt; const float pos = userow ? (float)(sp >> 6) : (float)(sp & 63);
;                 float cs[4], sn[4], ga[4], gb[4];
;                 { const float* gp = g + t0; asm volatile("" : "+v"(gp));
;                   const f32x4 g1 = *(const f32x4*)gp, g2 = *(const f32x4*)(gp + hd2);
; #pragma unroll
;                   for (int p = 0; p < 4; ++p) { ga[p] = g1[p] * osc; gb[p] = g2[p] * osc; } }
; #pragma unroll
;                 for (int p = 0; p < 4; ++p) { const float ang = pos * __builtin_amdgcn_exp2f(-(float)((t0 + p) & (nf - 1)) * (13.287712379549449f / (float)nf));
;                     cs[p] = rope ? __cosf(ang) : 1.f; sn[p] = rope ? __sinf(ang) : 0.f; }
;                 bf16_t* rowp = base + (size_t)(rowbase + rt) * ld + col0;
; #pragma unroll
;                 for (int bj = 0; bj < 2; ++bj) { const f32x4 xs = *(const LAS f32x4*)(X + (rt * 2 + bj) * 4);
;                     const float tot = h128 ? ((xs[0] + xs[1]) + (xs[2] + xs[3])) : ((wc & 2) ? (xs[2] + xs[3]) : (xs[0] + xs[1]));
;                     const float rstd = rsqrtf(tot * inv_w + EPS);
;                     const f32x4 v0 = acc[ai][bj][m][0], v1 = acc[ai][bj][m][1];
;                     float o[8]; const float e[8] = {v0[0], v0[1], v0[2], v0[3], v1[0], v1[1], v1[2], v1[3]};
; #pragma unroll
;                     for (int p = 0; p < 4; ++p) { const float x1 = e[2 * p] * rstd * ga[p], x2 = e[2 * p + 1] * rstd * gb[p];
;                         o[2 * p] = x1 * cs[p] - x2 * sn[p]; o[2 * p + 1] = x2 * cs[p] + x1 * sn[p]; }
;                     *(u32x4*)(rowp + bj * HALF) = pack8(o); }
;                 EPI_FENCE(); __builtin_amdgcn_sched_barrier(0); }
.LBB0_388:
	s_waitcnt lgkmcnt(0)
	v_add_u32_e32 v136, s87, v186
	v_ashrrev_i32_e32 v136, 6, v136
	v_cvt_f32_i32_e32 v136, v136
	s_nop 0
	v_mul_f32_e32 v177, s43, v128
	v_mul_f32_e32 v139, s43, v129
	v_mul_f32_e32 v137, s43, v134
	v_cndmask_b32_e64 v184, v175, v136, s[8:9]
	v_mul_f32_e32 v128, v184, v155
	v_mul_f32_e32 v128, 0.15915494, v128
	v_cos_f32_e32 v129, v128
	v_sin_f32_e32 v128, v128
	v_mul_f32_e32 v134, s43, v135
	v_mul_f32_e32 v175, s43, v132
	v_cndmask_b32_e64 v135, 1.0, v129, s[6:7]
	v_cndmask_b32_e64 v178, 0, v128, s[6:7]
	v_mul_f32_e32 v128, v184, v161
	v_mul_f32_e32 v128, 0.15915494, v128
	v_cos_f32_e32 v129, v128
	v_sin_f32_e32 v128, v128
	v_mul_f32_e32 v173, s43, v133
	v_mul_f32_e32 v138, s43, v130
	v_cndmask_b32_e64 v179, 1.0, v129, s[6:7]
	v_cndmask_b32_e64 v182, 0, v128, s[6:7]
	v_mul_f32_e32 v128, v184, v172
	v_mul_f32_e32 v128, 0.15915494, v128
	v_cos_f32_e32 v129, v128
	v_sin_f32_e32 v128, v128
	v_mul_f32_e32 v136, s43, v131
	v_cndmask_b32_e64 v181, 1.0, v129, s[6:7]
	v_cndmask_b32_e64 v183, 0, v128, s[6:7]
	v_mul_f32_e32 v128, v184, v160
	v_mul_f32_e32 v128, 0.15915494, v128
	v_cos_f32_e32 v129, v128
	v_sin_f32_e32 v128, v128
	v_cndmask_b32_e64 v184, 1.0, v129, s[6:7]
	v_cndmask_b32_e64 v185, 0, v128, s[6:7]
	v_add_u32_e32 v128, s35, v186
	v_mad_i64_i32 v[128:129], s[0:1], s86, v128, 0
	v_lshl_add_u64 v[132:133], v[128:129], 1, v[156:157]
	v_fma_f32 v128, s45, v187, v168
	v_cmp_gt_f32_e32 vcc, s85, v128
	v_mul_f32_e32 v129, 0x4b800000, v128
	s_mov_b64 s[0:1], -1
	v_cndmask_b32_e32 v128, v128, v129, vcc
	v_rsq_f32_e32 v128, v128
	s_nop 0
	v_mul_f32_e32 v129, 0x45800000, v128
	v_cndmask_b32_e32 v128, v128, v129, vcc
	v_mul_f32_e32 v130, v45, v128
	v_mul_f32_e32 v129, v44, v128
	v_mul_f32_e32 v130, v175, v130
	v_mul_f32_e32 v129, v177, v129
	v_mul_f32_e32 v131, v178, v130
	v_mul_f32_e32 v130, v135, v130
	v_mul_f32_e32 v186, v47, v128
	v_fma_f32 v131, v135, v129, -v131
	v_fmac_f32_e32 v130, v178, v129
	v_mul_f32_e32 v129, v46, v128
	v_mul_f32_e32 v186, v173, v186
	v_mul_f32_e32 v129, v139, v129
	v_mul_f32_e32 v187, v182, v186
	v_mul_f32_e32 v186, v179, v186
	v_mul_f32_e32 v188, v41, v128
	v_fma_f32 v187, v179, v129, -v187
	v_fmac_f32_e32 v186, v182, v129
	v_mul_f32_e32 v129, v40, v128
	v_mul_f32_e32 v188, v137, v188
	v_mul_f32_e32 v129, v138, v129
	v_mul_f32_e32 v189, v183, v188
	v_mul_f32_e32 v188, v181, v188
	v_fma_f32 v189, v181, v129, -v189
	v_fmac_f32_e32 v188, v183, v129
	v_mul_f32_e32 v129, v42, v128
	v_mul_f32_e32 v128, v43, v128
	v_mul_f32_e32 v128, v134, v128
	v_mul_f32_e32 v129, v136, v129
	v_mul_f32_e32 v190, v185, v128
	v_mul_f32_e32 v191, v184, v128
	v_cvt_pk_bf16_f32 v128, v131, v130
	v_fma_f32 v190, v184, v129, -v190
	v_fmac_f32_e32 v191, v185, v129
	v_cvt_pk_bf16_f32 v129, v187, v186
	v_cvt_pk_bf16_f32 v130, v189, v188
	v_cvt_pk_bf16_f32 v131, v190, v191
	global_store_dwordx4 v[132:133], v[128:131], off nt
	s_and_b64 vcc, exec, s[2:3]
	s_nop 0
	v_add_u32_e32 v128, s95, v180
	ds_read_b128 v[128:131], v128 offset:16
	s_cbranch_vccnz .LBB0_394
	s_and_b64 vcc, exec, s[4:5]
	s_cbranch_vccnz .LBB0_391
	s_waitcnt lgkmcnt(0)
	v_add_f32_e32 v180, v130, v131
	s_mov_b64 s[0:1], 0

; #define LAS __attribute__((address_space(3)))
;     __device__ __forceinline__ void operator()(const Acc& acc, const Unit& u, int wr, int wc, int fr_, int fq_) const {
;     ...
;             for (int m = 0; m < 4; ++m) { const int rt = ai * HALF + wr * 64 + m * 16 + fr;
;                 const int sp = (u.pm & 15) * BM + rt; const float pos = userow ? (float)(sp >> 6) : (float)(sp & 63);
;                 float cs[4], sn[4], ga[4], gb[4];
;                 { const float* gp = g + t0; asm volatile("" : "+v"(gp));
;                   const f32x4 g1 = *(const f32x4*)gp, g2 = *(const f32x4*)(gp + hd2);
; #pragma unroll
;                   for (int p = 0; p < 4; ++p) { ga[p] = g1[p] * osc; gb[p] = g2[p] * osc; } }
; #pragma unroll
;                 for (int p = 0; p < 4; ++p) { const float ang = pos * __builtin_amdgcn_exp2f(-(float)((t0 + p) & (nf - 1)) * (13.287712379549449f / (float)nf));
;                     cs[p] = rope ? __cosf(ang) : 1.f; sn[p] = rope ? __sinf(ang) : 0.f; }
;                 bf16_t* rowp = base + (size_t)(rowbase + rt) * ld + col0;
; #pragma unroll
;                 for (int bj = 0; bj < 2; ++bj) { const f32x4 xs = *(const LAS f32x4*)(X + (rt * 2 + bj) * 4);
;                     const float tot = h128 ? ((xs[0] + xs[1]) + (xs[2] + xs[3])) : ((wc & 2) ? (xs[2] + xs[3]) : (xs[0] + xs[1]));
;                     const float rstd = rsqrtf(tot * inv_w + EPS);
;                     const f32x4 v0 = acc[ai][bj][m][0], v1 = acc[ai][bj][m][1];
;                     float o[8]; const float e[8] = {v0[0], v0[1], v0[2], v0[3], v1[0], v1[1], v1[2], v1[3]};
; #pragma unroll
;                     for (int p = 0; p < 4; ++p) { const float x1 = e[2 * p] * rstd * ga[p], x2 = e[2 * p + 1] * rstd * gb[p];
;                         o[2 * p] = x1 * cs[p] - x2 * sn[p]; o[2 * p + 1] = x2 * cs[p] + x1 * sn[p]; }
;                     *(u32x4*)(rowp + bj * HALF) = pack8(o); }
.LBB0_396:
	s_waitcnt lgkmcnt(0)
	v_fma_f32 v128, s45, v180, v168
	v_cmp_gt_f32_e32 vcc, s85, v128
	v_mul_f32_e32 v129, 0x4b800000, v128
	s_nop 0
	v_cndmask_b32_e32 v128, v128, v129, vcc
	v_rsq_f32_e32 v128, v128
	s_nop 0
	v_mul_f32_e32 v129, 0x45800000, v128
	v_cndmask_b32_e32 v128, v128, v129, vcc
	v_mul_f32_e32 v130, v37, v128
	v_mul_f32_e32 v129, v36, v128
	v_mul_f32_e32 v130, v175, v130
	v_mul_f32_e32 v129, v177, v129
	v_mul_f32_e32 v131, v178, v130
	v_fma_f32 v131, v135, v129, -v131
	v_mul_f32_e32 v130, v135, v130
	v_mul_f32_e32 v135, v39, v128
	v_fmac_f32_e32 v130, v178, v129
	v_mul_f32_e32 v129, v38, v128
	v_mul_f32_e32 v135, v173, v135
	v_mul_f32_e32 v129, v139, v129
	v_mul_f32_e32 v139, v182, v135
	v_mul_f32_e32 v135, v179, v135
	v_fma_f32 v139, v179, v129, -v139
	v_fmac_f32_e32 v135, v182, v129
	v_mul_f32_e32 v129, v32, v128
	v_mul_f32_e32 v129, v138, v129
	v_mul_f32_e32 v138, v33, v128
	v_mul_f32_e32 v137, v137, v138
	v_mul_f32_e32 v138, v183, v137
	v_mul_f32_e32 v137, v181, v137
	v_fma_f32 v138, v181, v129, -v138
	v_fmac_f32_e32 v137, v183, v129
	v_mul_f32_e32 v129, v34, v128
	v_mul_f32_e32 v128, v35, v128
	v_mul_f32_e32 v128, v134, v128
	v_mul_f32_e32 v129, v136, v129
	v_mul_f32_e32 v134, v185, v128
	v_mul_f32_e32 v136, v184, v128
	v_fma_f32 v134, v184, v129, -v134
	v_fmac_f32_e32 v136, v185, v129
	v_cvt_pk_bf16_f32 v128, v131, v130
	v_cvt_pk_bf16_f32 v129, v139, v135
	v_cvt_pk_bf16_f32 v130, v138, v137
	v_cvt_pk_bf16_f32 v131, v134, v136
	global_store_dwordx4 v[132:133], v[128:131], off offset:256 nt
	s_nop 1
	v_mov_b64_e32 v[128:129], v[158:159]
	v_add_u32_e32 v185, 0xa0, v171
	v_lshl_add_u64 v[132:133], v[128:129], 0, s[22:23]
	v_mov_b32_e32 v128, v194
	v_mov_b32_e32 v129, v195
	v_mov_b32_e32 v130, v196
	v_mov_b32_e32 v131, v197
	v_mov_b32_e32 v132, v198
	v_mov_b32_e32 v133, v199
	v_mov_b32_e32 v134, v200
	v_mov_b32_e32 v135, v201
	v_lshlrev_b32_e32 v179, 5, v185
	v_add_u32_e32 v136, 0, v179
	v_add_u32_e32 v136, 0x20000, v136
	ds_read_b128 v[136:139], v136
	s_and_b64 vcc, exec, s[2:3]
	s_mov_b64 s[0:1], -1
	s_cbranch_vccnz .LBB0_402
	s_and_b64 vcc, exec, s[4:5]
	s_cbranch_vccnz .LBB0_399
	s_waitcnt lgkmcnt(0)
	v_add_f32_e32 v186, v138, v139
	s_mov_b64 s[0:1], 0

; #define LAS __attribute__((address_space(3)))
;     __device__ __forceinline__ void operator()(const Acc& acc, const Unit& u, int wr, int wc, int fr_, int fq_) const {
;     ...
;             for (int m = 0; m < 4; ++m) { const int rt = ai * HALF + wr * 64 + m * 16 + fr;
;                 const int sp = (u.pm & 15) * BM + rt; const float pos = userow ? (float)(sp >> 6) : (float)(sp & 63);
;                 float cs[4], sn[4], ga[4], gb[4];
;                 { const float* gp = g + t0; asm volatile("" : "+v"(gp));
;                   const f32x4 g1 = *(const f32x4*)gp, g2 = *(const f32x4*)(gp + hd2);
; #pragma unroll
;                   for (int p = 0; p < 4; ++p) { ga[p] = g1[p] * osc; gb[p] = g2[p] * osc; } }
; #pragma unroll
;                 for (int p = 0; p < 4; ++p) { const float ang = pos * __builtin_amdgcn_exp2f(-(float)((t0 + p) & (nf - 1)) * (13.287712379549449f / (float)nf));
;                     cs[p] = rope ? __cosf(ang) : 1.f; sn[p] = rope ? __sinf(ang) : 0.f; }
;                 bf16_t* rowp = base + (size_t)(rowbase + rt) * ld + col0;
; #pragma unroll
;                 for (int bj = 0; bj < 2; ++bj) { const f32x4 xs = *(const LAS f32x4*)(X + (rt * 2 + bj) * 4);
;                     const float tot = h128 ? ((xs[0] + xs[1]) + (xs[2] + xs[3])) : ((wc & 2) ? (xs[2] + xs[3]) : (xs[0] + xs[1]));
;                     const float rstd = rsqrtf(tot * inv_w + EPS);
;                     const f32x4 v0 = acc[ai][bj][m][0], v1 = acc[ai][bj][m][1];
;                     float o[8]; const float e[8] = {v0[0], v0[1], v0[2], v0[3], v1[0], v1[1], v1[2], v1[3]};
; #pragma unroll
;                     for (int p = 0; p < 4; ++p) { const float x1 = e[2 * p] * rstd * ga[p], x2 = e[2 * p + 1] * rstd * gb[p];
;                         o[2 * p] = x1 * cs[p] - x2 * sn[p]; o[2 * p + 1] = x2 * cs[p] + x1 * sn[p]; }
;                     *(u32x4*)(rowp + bj * HALF) = pack8(o); }
.LBB0_404:
	s_waitcnt lgkmcnt(0)
	v_add_u32_e32 v136, s87, v185
	v_ashrrev_i32_e32 v136, 6, v136
	v_cvt_f32_i32_e32 v136, v136
	s_nop 0
	v_mul_f32_e32 v175, s43, v128
	v_mul_f32_e32 v139, s43, v129
	v_mul_f32_e32 v137, s43, v134
	v_cndmask_b32_e64 v183, v174, v136, s[8:9]
	v_mul_f32_e32 v128, v183, v155
	v_mul_f32_e32 v128, 0.15915494, v128
	v_cos_f32_e32 v129, v128
	v_sin_f32_e32 v128, v128
	v_mul_f32_e32 v134, s43, v135
	v_mul_f32_e32 v174, s43, v132
	v_cndmask_b32_e64 v135, 1.0, v129, s[6:7]
	v_cndmask_b32_e64 v177, 0, v128, s[6:7]
	v_mul_f32_e32 v128, v183, v161
	v_mul_f32_e32 v128, 0.15915494, v128
	v_cos_f32_e32 v129, v128
	v_sin_f32_e32 v128, v128
	v_mul_f32_e32 v173, s43, v133
	v_mul_f32_e32 v138, s43, v130
	v_cndmask_b32_e64 v178, 1.0, v129, s[6:7]
	v_cndmask_b32_e64 v181, 0, v128, s[6:7]
	v_mul_f32_e32 v128, v183, v172
	v_mul_f32_e32 v128, 0.15915494, v128
	v_cos_f32_e32 v129, v128
	v_sin_f32_e32 v128, v128
	v_mul_f32_e32 v136, s43, v131
	v_cndmask_b32_e64 v180, 1.0, v129, s[6:7]
	v_cndmask_b32_e64 v182, 0, v128, s[6:7]
	v_mul_f32_e32 v128, v183, v160
	v_mul_f32_e32 v128, 0.15915494, v128
	v_cos_f32_e32 v129, v128
	v_sin_f32_e32 v128, v128
	v_cndmask_b32_e64 v183, 1.0, v129, s[6:7]
	v_cndmask_b32_e64 v184, 0, v128, s[6:7]
	v_add_u32_e32 v128, s35, v185
	v_mad_i64_i32 v[128:129], s[0:1], s86, v128, 0
	v_lshl_add_u64 v[132:133], v[128:129], 1, v[156:157]
	v_fma_f32 v128, s45, v186, v168
	v_cmp_gt_f32_e32 vcc, s85, v128
	v_mul_f32_e32 v129, 0x4b800000, v128
	s_mov_b64 s[0:1], -1
	v_cndmask_b32_e32 v128, v128, v129, vcc
	v_rsq_f32_e32 v128, v128
	s_nop 0
	v_mul_f32_e32 v129, 0x45800000, v128
	v_cndmask_b32_e32 v128, v128, v129, vcc
	v_mul_f32_e32 v130, v29, v128
	v_mul_f32_e32 v129, v28, v128
	v_mul_f32_e32 v130, v174, v130
	v_mul_f32_e32 v129, v175, v129
	v_mul_f32_e32 v131, v177, v130
	v_mul_f32_e32 v130, v135, v130
	v_mul_f32_e32 v185, v31, v128
	v_fma_f32 v131, v135, v129, -v131
	v_fmac_f32_e32 v130, v177, v129
	v_mul_f32_e32 v129, v30, v128
	v_mul_f32_e32 v185, v173, v185
	v_mul_f32_e32 v129, v139, v129
	v_mul_f32_e32 v186, v181, v185
	v_mul_f32_e32 v185, v178, v185
	v_mul_f32_e32 v187, v25, v128
	v_fma_f32 v186, v178, v129, -v186
	v_fmac_f32_e32 v185, v181, v129
	v_mul_f32_e32 v129, v24, v128
	v_mul_f32_e32 v187, v137, v187
	v_mul_f32_e32 v129, v138, v129
	v_mul_f32_e32 v188, v182, v187
	v_mul_f32_e32 v187, v180, v187
	v_fma_f32 v188, v180, v129, -v188
	v_fmac_f32_e32 v187, v182, v129
	v_mul_f32_e32 v129, v26, v128
	v_mul_f32_e32 v128, v27, v128
	v_mul_f32_e32 v128, v134, v128
	v_mul_f32_e32 v129, v136, v129
	v_mul_f32_e32 v189, v184, v128
	v_mul_f32_e32 v190, v183, v128
	v_cvt_pk_bf16_f32 v128, v131, v130
	v_fma_f32 v189, v183, v129, -v189
	v_fmac_f32_e32 v190, v184, v129
	v_cvt_pk_bf16_f32 v129, v186, v185
	v_cvt_pk_bf16_f32 v130, v188, v187
	v_cvt_pk_bf16_f32 v131, v189, v190
	global_store_dwordx4 v[132:133], v[128:131], off nt
	s_and_b64 vcc, exec, s[2:3]
	s_nop 0
	v_add_u32_e32 v128, s95, v179
	ds_read_b128 v[128:131], v128 offset:16
	s_cbranch_vccnz .LBB0_410
	s_and_b64 vcc, exec, s[4:5]
	s_cbranch_vccnz .LBB0_407
	s_waitcnt lgkmcnt(0)
	v_add_f32_e32 v179, v130, v131
	s_mov_b64 s[0:1], 0

; #define LAS __attribute__((address_space(3)))
;     __device__ __forceinline__ void operator()(const Acc& acc, const Unit& u, int wr, int wc, int fr_, int fq_) const {
;     ...
;             for (int m = 0; m < 4; ++m) { const int rt = ai * HALF + wr * 64 + m * 16 + fr;
;                 const int sp = (u.pm & 15) * BM + rt; const float pos = userow ? (float)(sp >> 6) : (float)(sp & 63);
;                 float cs[4], sn[4], ga[4], gb[4];
;                 { const float* gp = g + t0; asm volatile("" : "+v"(gp));
;                   const f32x4 g1 = *(const f32x4*)gp, g2 = *(const f32x4*)(gp + hd2);
; #pragma unroll
;                   for (int p = 0; p < 4; ++p) { ga[p] = g1[p] * osc; gb[p] = g2[p] * osc; } }
; #pragma unroll
;                 for (int p = 0; p < 4; ++p) { const float ang = pos * __builtin_amdgcn_exp2f(-(float)((t0 + p) & (nf - 1)) * (13.287712379549449f / (float)nf));
;                     cs[p] = rope ? __cosf(ang) : 1.f; sn[p] = rope ? __sinf(ang) : 0.f; }
;                 bf16_t* rowp = base + (size_t)(rowbase + rt) * ld + col0;
; #pragma unroll
;                 for (int bj = 0; bj < 2; ++bj) { const f32x4 xs = *(const LAS f32x4*)(X + (rt * 2 + bj) * 4);
;                     const float tot = h128 ? ((xs[0] + xs[1]) + (xs[2] + xs[3])) : ((wc & 2) ? (xs[2] + xs[3]) : (xs[0] + xs[1]));
;                     const float rstd = rsqrtf(tot * inv_w + EPS);
;                     const f32x4 v0 = acc[ai][bj][m][0], v1 = acc[ai][bj][m][1];
;                     float o[8]; const float e[8] = {v0[0], v0[1], v0[2], v0[3], v1[0], v1[1], v1[2], v1[3]};
; #pragma unroll
;                     for (int p = 0; p < 4; ++p) { const float x1 = e[2 * p] * rstd * ga[p], x2 = e[2 * p + 1] * rstd * gb[p];
;                         o[2 * p] = x1 * cs[p] - x2 * sn[p]; o[2 * p + 1] = x2 * cs[p] + x1 * sn[p]; }
;                     *(u32x4*)(rowp + bj * HALF) = pack8(o); }
.LBB0_412:
	s_waitcnt lgkmcnt(0)
	v_fma_f32 v128, s45, v179, v168
	v_cmp_gt_f32_e32 vcc, s85, v128
	v_mul_f32_e32 v129, 0x4b800000, v128
	s_nop 0
	v_cndmask_b32_e32 v128, v128, v129, vcc
	v_rsq_f32_e32 v128, v128
	s_nop 0
	v_mul_f32_e32 v129, 0x45800000, v128
	v_cndmask_b32_e32 v128, v128, v129, vcc
	v_mul_f32_e32 v130, v21, v128
	v_mul_f32_e32 v129, v20, v128
	v_mul_f32_e32 v130, v174, v130
	v_mul_f32_e32 v129, v175, v129
	v_mul_f32_e32 v131, v177, v130
	v_fma_f32 v131, v135, v129, -v131
	v_mul_f32_e32 v130, v135, v130
	v_mul_f32_e32 v135, v23, v128
	v_fmac_f32_e32 v130, v177, v129
	v_mul_f32_e32 v129, v22, v128
	v_mul_f32_e32 v135, v173, v135
	v_mul_f32_e32 v129, v139, v129
	v_mul_f32_e32 v139, v181, v135
	v_mul_f32_e32 v135, v178, v135
	v_fma_f32 v139, v178, v129, -v139
	v_fmac_f32_e32 v135, v181, v129
	v_mul_f32_e32 v129, v16, v128
	v_mul_f32_e32 v129, v138, v129
	v_mul_f32_e32 v138, v17, v128
	v_mul_f32_e32 v137, v137, v138
	v_mul_f32_e32 v138, v182, v137
	v_mul_f32_e32 v137, v180, v137
	v_fma_f32 v138, v180, v129, -v138
	v_fmac_f32_e32 v137, v182, v129
	v_mul_f32_e32 v129, v18, v128
	v_mul_f32_e32 v128, v19, v128
	v_mul_f32_e32 v128, v134, v128
	v_mul_f32_e32 v129, v136, v129
	v_mul_f32_e32 v134, v184, v128
	v_mul_f32_e32 v136, v183, v128
	v_fma_f32 v134, v183, v129, -v134
	v_fmac_f32_e32 v136, v184, v129
	v_cvt_pk_bf16_f32 v128, v131, v130
	v_cvt_pk_bf16_f32 v129, v139, v135
	v_cvt_pk_bf16_f32 v130, v138, v137
	v_cvt_pk_bf16_f32 v131, v134, v136
	global_store_dwordx4 v[132:133], v[128:131], off offset:256 nt
	v_add_u32_e32 v177, 0xb0, v171
	v_lshl_add_u64 v[132:133], v[158:159], 0, s[22:23]
	v_mov_b32_e32 v128, v194
	v_mov_b32_e32 v129, v195
	v_mov_b32_e32 v130, v196
	v_mov_b32_e32 v131, v197
	v_mov_b32_e32 v132, v198
	v_mov_b32_e32 v133, v199
	v_mov_b32_e32 v134, v200
	v_mov_b32_e32 v135, v201
	v_lshlrev_b32_e32 v173, 5, v177
	v_add_u32_e32 v136, 0, v173
	v_add_u32_e32 v136, 0x20000, v136
	ds_read_b128 v[136:139], v136
	s_and_b64 vcc, exec, s[2:3]
	s_mov_b64 s[0:1], -1
	s_cbranch_vccnz .LBB0_418
	s_and_b64 vcc, exec, s[4:5]
	s_cbranch_vccnz .LBB0_415
	s_waitcnt lgkmcnt(0)
	v_add_f32_e32 v178, v138, v139
	s_mov_b64 s[0:1], 0

; #define LAS __attribute__((address_space(3)))
;     __device__ __forceinline__ void operator()(const Acc& acc, const Unit& u, int wr, int wc, int fr_, int fq_) const {
;     ...
;             for (int m = 0; m < 4; ++m) { const int rt = ai * HALF + wr * 64 + m * 16 + fr;
;                 const int sp = (u.pm & 15) * BM + rt; const float pos = userow ? (float)(sp >> 6) : (float)(sp & 63);
;                 float cs[4], sn[4], ga[4], gb[4];
;                 { const float* gp = g + t0; asm volatile("" : "+v"(gp));
;                   const f32x4 g1 = *(const f32x4*)gp, g2 = *(const f32x4*)(gp + hd2);
; #pragma unroll
;                   for (int p = 0; p < 4; ++p) { ga[p] = g1[p] * osc; gb[p] = g2[p] * osc; } }
; #pragma unroll
;                 for (int p = 0; p < 4; ++p) { const float ang = pos * __builtin_amdgcn_exp2f(-(float)((t0 + p) & (nf - 1)) * (13.287712379549449f / (float)nf));
;                     cs[p] = rope ? __cosf(ang) : 1.f; sn[p] = rope ? __sinf(ang) : 0.f; }
;                 bf16_t* rowp = base + (size_t)(rowbase + rt) * ld + col0;
; #pragma unroll
;                 for (int bj = 0; bj < 2; ++bj) { const f32x4 xs = *(const LAS f32x4*)(X + (rt * 2 + bj) * 4);
;                     const float tot = h128 ? ((xs[0] + xs[1]) + (xs[2] + xs[3])) : ((wc & 2) ? (xs[2] + xs[3]) : (xs[0] + xs[1]));
;                     const float rstd = rsqrtf(tot * inv_w + EPS);
;                     const f32x4 v0 = acc[ai][bj][m][0], v1 = acc[ai][bj][m][1];
;                     float o[8]; const float e[8] = {v0[0], v0[1], v0[2], v0[3], v1[0], v1[1], v1[2], v1[3]};
; #pragma unroll
;                     for (int p = 0; p < 4; ++p) { const float x1 = e[2 * p] * rstd * ga[p], x2 = e[2 * p + 1] * rstd * gb[p];
;                         o[2 * p] = x1 * cs[p] - x2 * sn[p]; o[2 * p + 1] = x2 * cs[p] + x1 * sn[p]; }
;                     *(u32x4*)(rowp + bj * HALF) = pack8(o); }
.LBB0_420:
	s_waitcnt lgkmcnt(0)
	v_add_u32_e32 v136, s87, v177
	v_ashrrev_i32_e32 v136, 6, v136
	v_cvt_f32_i32_e32 v136, v136
	s_nop 0
	v_mul_f32_e32 v171, s43, v128
	v_mul_f32_e32 v139, s43, v129
	v_mul_f32_e32 v137, s43, v134
	v_cndmask_b32_e64 v176, v176, v136, s[8:9]
	v_mul_f32_e32 v128, v176, v155
	v_mul_f32_e32 v128, 0.15915494, v128
	v_cos_f32_e32 v129, v128
	v_sin_f32_e32 v128, v128
	v_mul_f32_e32 v134, s43, v135
	v_mul_f32_e32 v159, s43, v132
	v_cndmask_b32_e64 v135, 1.0, v129, s[6:7]
	v_cndmask_b32_e64 v155, 0, v128, s[6:7]
	v_mul_f32_e32 v128, v176, v161
	v_mul_f32_e32 v128, 0.15915494, v128
	v_cos_f32_e32 v129, v128
	v_sin_f32_e32 v128, v128
	v_mul_f32_e32 v158, s43, v133
	v_mul_f32_e32 v138, s43, v130
	v_cndmask_b32_e64 v161, 1.0, v129, s[6:7]
	v_cndmask_b32_e64 v174, 0, v128, s[6:7]
	v_mul_f32_e32 v128, v176, v172
	v_mul_f32_e32 v128, 0.15915494, v128
	v_cos_f32_e32 v129, v128
	v_sin_f32_e32 v128, v128
	v_mul_f32_e32 v136, s43, v131
	v_cndmask_b32_e64 v172, 1.0, v129, s[6:7]
	v_cndmask_b32_e64 v175, 0, v128, s[6:7]
	v_mul_f32_e32 v128, v176, v160
	v_mul_f32_e32 v128, 0.15915494, v128
	v_cos_f32_e32 v129, v128
	v_sin_f32_e32 v128, v128
	v_cndmask_b32_e64 v160, 1.0, v129, s[6:7]
	v_cndmask_b32_e64 v176, 0, v128, s[6:7]
	v_add_u32_e32 v128, s35, v177
	v_mad_i64_i32 v[128:129], s[0:1], s86, v128, 0
	v_lshl_add_u64 v[132:133], v[128:129], 1, v[156:157]
	v_fma_f32 v128, s45, v178, v168
	v_cmp_gt_f32_e32 vcc, s85, v128
	v_mul_f32_e32 v129, 0x4b800000, v128
	s_mov_b64 s[0:1], -1
	v_cndmask_b32_e32 v128, v128, v129, vcc
	v_rsq_f32_e32 v128, v128
	s_nop 0
	v_mul_f32_e32 v129, 0x45800000, v128
	v_cndmask_b32_e32 v128, v128, v129, vcc
	v_mul_f32_e32 v130, v13, v128
	v_mul_f32_e32 v129, v12, v128
	v_mul_f32_e32 v130, v159, v130
	v_mul_f32_e32 v129, v171, v129
	v_mul_f32_e32 v131, v155, v130
	v_mul_f32_e32 v130, v135, v130
	v_mul_f32_e32 v156, v15, v128
	v_fma_f32 v131, v135, v129, -v131
	v_fmac_f32_e32 v130, v155, v129
	v_mul_f32_e32 v129, v14, v128
	v_mul_f32_e32 v156, v158, v156
	v_mul_f32_e32 v129, v139, v129
	v_mul_f32_e32 v157, v174, v156
	v_mul_f32_e32 v156, v161, v156
	v_mul_f32_e32 v177, v9, v128
	v_fma_f32 v157, v161, v129, -v157
	v_fmac_f32_e32 v156, v174, v129
	v_mul_f32_e32 v129, v8, v128
	v_mul_f32_e32 v177, v137, v177
	v_mul_f32_e32 v129, v138, v129
	v_mul_f32_e32 v178, v175, v177
	v_mul_f32_e32 v177, v172, v177
	v_fma_f32 v178, v172, v129, -v178
	v_fmac_f32_e32 v177, v175, v129
	v_mul_f32_e32 v129, v10, v128
	v_mul_f32_e32 v128, v11, v128
	v_mul_f32_e32 v128, v134, v128
	v_mul_f32_e32 v129, v136, v129
	v_mul_f32_e32 v179, v176, v128
	v_mul_f32_e32 v180, v160, v128
	v_cvt_pk_bf16_f32 v128, v131, v130
	v_fma_f32 v179, v160, v129, -v179
	v_fmac_f32_e32 v180, v176, v129
	v_cvt_pk_bf16_f32 v129, v157, v156
	v_cvt_pk_bf16_f32 v130, v178, v177
	v_cvt_pk_bf16_f32 v131, v179, v180
	global_store_dwordx4 v[132:133], v[128:131], off nt
	s_and_b64 vcc, exec, s[2:3]
	s_nop 0
	v_add_u32_e32 v128, s95, v173
	ds_read_b128 v[128:131], v128 offset:16
	s_cbranch_vccnz .LBB0_426
	s_and_b64 vcc, exec, s[4:5]
	s_cbranch_vccnz .LBB0_423
	s_waitcnt lgkmcnt(0)
	v_add_f32_e32 v156, v130, v131
	s_mov_b64 s[0:1], 0

; #define LAS __attribute__((address_space(3)))
; #define EPI_FENCE() asm volatile("" ::: "memory")
;     __device__ __forceinline__ void operator()(const Acc& acc, const Unit& u, int wr, int wc, int fr_, int fq_) const {
;     ...
;                 bf16_t* rowp = base + (size_t)(rowbase + rt) * ld + col0;
; #pragma unroll
;                 for (int bj = 0; bj < 2; ++bj) { const f32x4 xs = *(const LAS f32x4*)(X + (rt * 2 + bj) * 4);
;                     const float tot = h128 ? ((xs[0] + xs[1]) + (xs[2] + xs[3])) : ((wc & 2) ? (xs[2] + xs[3]) : (xs[0] + xs[1]));
;                     const float rstd = rsqrtf(tot * inv_w + EPS);
;                     const f32x4 v0 = acc[ai][bj][m][0], v1 = acc[ai][bj][m][1];
;                     float o[8]; const float e[8] = {v0[0], v0[1], v0[2], v0[3], v1[0], v1[1], v1[2], v1[3]};
; #pragma unroll
;                     for (int p = 0; p < 4; ++p) { const float x1 = e[2 * p] * rstd * ga[p], x2 = e[2 * p + 1] * rstd * gb[p];
;                         o[2 * p] = x1 * cs[p] - x2 * sn[p]; o[2 * p + 1] = x2 * cs[p] + x1 * sn[p]; }
;                     *(u32x4*)(rowp + bj * HALF) = pack8(o); }
;                 EPI_FENCE(); __builtin_amdgcn_sched_barrier(0); }
.LBB0_428:
	s_waitcnt lgkmcnt(0)
	v_fma_f32 v128, s45, v156, v168
	v_cmp_gt_f32_e32 vcc, s85, v128
	v_mul_f32_e32 v129, 0x4b800000, v128
	s_nop 0
	v_cndmask_b32_e32 v128, v128, v129, vcc
	v_rsq_f32_e32 v128, v128
	s_nop 0
	v_mul_f32_e32 v129, 0x45800000, v128
	v_cndmask_b32_e32 v128, v128, v129, vcc
	v_mul_f32_e32 v130, v5, v128
	v_mul_f32_e32 v129, v4, v128
	v_mul_f32_e32 v130, v159, v130
	v_mul_f32_e32 v129, v171, v129
	v_mul_f32_e32 v131, v155, v130
	v_fma_f32 v131, v135, v129, -v131
	v_mul_f32_e32 v130, v135, v130
	v_mul_f32_e32 v135, v7, v128
	v_fmac_f32_e32 v130, v155, v129
	v_mul_f32_e32 v129, v6, v128
	v_mul_f32_e32 v135, v158, v135
	v_mul_f32_e32 v129, v139, v129
	v_mul_f32_e32 v139, v174, v135
	v_mul_f32_e32 v135, v161, v135
	v_fma_f32 v139, v161, v129, -v139
	v_fmac_f32_e32 v135, v174, v129
	v_mul_f32_e32 v129, v0, v128
	v_mul_f32_e32 v129, v138, v129
	v_mul_f32_e32 v138, v1, v128
	v_mul_f32_e32 v137, v137, v138
	v_mul_f32_e32 v138, v175, v137
	v_mul_f32_e32 v137, v172, v137
	v_fma_f32 v138, v172, v129, -v138
	v_fmac_f32_e32 v137, v175, v129
	v_mul_f32_e32 v129, v2, v128
	v_mul_f32_e32 v128, v3, v128
	v_mul_f32_e32 v128, v134, v128
	v_mul_f32_e32 v129, v136, v129
	v_mul_f32_e32 v134, v176, v128
	v_mul_f32_e32 v136, v160, v128
	v_fma_f32 v134, v160, v129, -v134
	v_fmac_f32_e32 v136, v176, v129
	v_cvt_pk_bf16_f32 v128, v131, v130
	v_cvt_pk_bf16_f32 v129, v139, v135
	v_cvt_pk_bf16_f32 v130, v138, v137
	v_cvt_pk_bf16_f32 v131, v134, v136
	global_store_dwordx4 v[132:133], v[128:131], off offset:256 nt
	s_mov_b64 s[2:3], 0

; __device__ __forceinline__ unsigned cvt_pk_bf16(float lo, float hi) { unsigned r; asm volatile("v_cvt_pk_bf16_f32 %0, %1, %2" : "=v"(r) : "v"(lo), "v"(hi)); return r; }
; __device__ __forceinline__ float sigmoidf_(float x) { return __builtin_amdgcn_rcpf(1.0f + __builtin_amdgcn_exp2f(-1.4426950408889634f * x)); }
;     __device__ __forceinline__ void operator()(const Acc& acc, const Unit& u, int wr, int wc, int fr_, int fq_) const {
;     ...
;         if (hk == 0) {
; #pragma unroll
;             for (int ai = 0; ai < 2; ++ai)
; #pragma unroll
;                 for (int m = 0; m < 4; ++m) { bf16_t* rowp = base + (size_t)(row0 + ai * HALF + m * 16) * ld + col0;
; #pragma unroll
;                     for (int bj = 0; bj < 2; ++bj) { f32x4 v0 = acc[ai][bj][m][0], v1 = acc[ai][bj][m][1];
;                         if (sig) {
; #pragma unroll
;                             for (int j = 0; j < 4; ++j) { v0[j] = sigmoidf_(v0[j]); v1[j] = sigmoidf_(v1[j]); } }
;                         u32x4 w; w.x = cvt_pk_bf16(v0[0], v0[1]); w.y = cvt_pk_bf16(v0[2], v0[3]); w.z = cvt_pk_bf16(v1[0], v1[1]); w.w = cvt_pk_bf16(v1[2], v1[3]);
;                         *(u32x4*)(rowp + bj * HALF) = w; } }
;             return;
.LBB0_432:
	s_add_i32 s35, s35, s93
	v_add_u32_e32 v132, s35, v170
	v_ashrrev_i32_e32 v155, 31, v154
	v_lshl_add_u64 v[128:129], v[154:155], 1, s[88:89]
	v_mad_i64_i32 v[130:131], s[0:1], s86, v132, 0
	v_lshl_add_u64 v[130:131], v[130:131], 1, v[128:129]
	s_and_b64 vcc, exec, s[2:3]
	v_cvt_pk_bf16_f32 v124, v124, v125
	v_cvt_pk_bf16_f32 v125, v126, v127
	v_cvt_pk_bf16_f32 v126, v120, v121
	v_cvt_pk_bf16_f32 v127, v122, v123
	global_store_dwordx4 v[130:131], v[124:127], off nt
	s_cbranch_vccnz .LBB0_434
	v_mul_f32_e32 v116, 0xbfb8aa3b, v116
	v_mul_f32_e32 v112, 0xbfb8aa3b, v112
	v_mul_f32_e32 v117, 0xbfb8aa3b, v117
	v_mul_f32_e32 v113, 0xbfb8aa3b, v113
	v_mul_f32_e32 v118, 0xbfb8aa3b, v118
	v_mul_f32_e32 v114, 0xbfb8aa3b, v114
	v_mul_f32_e32 v119, 0xbfb8aa3b, v119
	v_mul_f32_e32 v115, 0xbfb8aa3b, v115
	v_exp_f32_e32 v116, v116
	v_exp_f32_e32 v112, v112
	v_exp_f32_e32 v117, v117
	v_exp_f32_e32 v113, v113
	v_exp_f32_e32 v118, v118
	v_exp_f32_e32 v114, v114
	v_exp_f32_e32 v119, v119
	v_exp_f32_e32 v115, v115
	v_add_f32_e32 v116, 1.0, v116
	v_add_f32_e32 v112, 1.0, v112
	v_add_f32_e32 v117, 1.0, v117
	v_add_f32_e32 v113, 1.0, v113
	v_add_f32_e32 v118, 1.0, v118
	v_add_f32_e32 v114, 1.0, v114
	v_add_f32_e32 v119, 1.0, v119
	v_add_f32_e32 v115, 1.0, v115
	v_rcp_f32_e32 v116, v116
	v_rcp_f32_e32 v112, v112
	v_rcp_f32_e32 v117, v117
	v_rcp_f32_e32 v113, v113
	v_rcp_f32_e32 v118, v118
	v_rcp_f32_e32 v114, v114
	v_rcp_f32_e32 v119, v119
	v_rcp_f32_e32 v115, v115
.LBB0_434:
	s_and_b64 vcc, exec, s[2:3]
	v_cvt_pk_bf16_f32 v116, v116, v117
	v_cvt_pk_bf16_f32 v117, v118, v119
	v_cvt_pk_bf16_f32 v118, v112, v113
	v_cvt_pk_bf16_f32 v119, v114, v115
	global_store_dwordx4 v[130:131], v[116:119], off offset:256 nt
	s_cbranch_vccnz .LBB0_436
	v_mul_f32_e32 v108, 0xbfb8aa3b, v108
	v_mul_f32_e32 v104, 0xbfb8aa3b, v104
	v_mul_f32_e32 v109, 0xbfb8aa3b, v109
	v_mul_f32_e32 v105, 0xbfb8aa3b, v105
	v_mul_f32_e32 v110, 0xbfb8aa3b, v110
	v_mul_f32_e32 v106, 0xbfb8aa3b, v106
	v_mul_f32_e32 v111, 0xbfb8aa3b, v111
	v_mul_f32_e32 v107, 0xbfb8aa3b, v107
	v_exp_f32_e32 v108, v108
	v_exp_f32_e32 v104, v104
	v_exp_f32_e32 v109, v109
	v_exp_f32_e32 v105, v105
	v_exp_f32_e32 v110, v110
	v_exp_f32_e32 v106, v106
	v_exp_f32_e32 v111, v111
	v_exp_f32_e32 v107, v107
	v_add_f32_e32 v108, 1.0, v108
	v_add_f32_e32 v104, 1.0, v104
	v_add_f32_e32 v109, 1.0, v109
	v_add_f32_e32 v105, 1.0, v105
	v_add_f32_e32 v110, 1.0, v110
	v_add_f32_e32 v106, 1.0, v106
	v_add_f32_e32 v111, 1.0, v111
	v_add_f32_e32 v107, 1.0, v107
	v_rcp_f32_e32 v108, v108
	v_rcp_f32_e32 v104, v104
	v_rcp_f32_e32 v109, v109
	v_rcp_f32_e32 v105, v105
	v_rcp_f32_e32 v110, v110
	v_rcp_f32_e32 v106, v106
	v_rcp_f32_e32 v111, v111
	v_rcp_f32_e32 v107, v107
.LBB0_436:
	v_add_u32_e32 v112, 16, v132
	v_mad_i64_i32 v[112:113], s[0:1], s86, v112, 0
	v_lshl_add_u64 v[112:113], v[112:113], 1, v[128:129]
	s_and_b64 vcc, exec, s[2:3]
	v_cvt_pk_bf16_f32 v108, v108, v109
	v_cvt_pk_bf16_f32 v109, v110, v111
	v_cvt_pk_bf16_f32 v110, v104, v105
	v_cvt_pk_bf16_f32 v111, v106, v107
	global_store_dwordx4 v[112:113], v[108:111], off nt
	s_cbranch_vccnz .LBB0_438
	v_mul_f32_e32 v100, 0xbfb8aa3b, v100
	v_mul_f32_e32 v96, 0xbfb8aa3b, v96
	v_mul_f32_e32 v101, 0xbfb8aa3b, v101
	v_mul_f32_e32 v97, 0xbfb8aa3b, v97
	v_mul_f32_e32 v102, 0xbfb8aa3b, v102
	v_mul_f32_e32 v98, 0xbfb8aa3b, v98
	v_mul_f32_e32 v103, 0xbfb8aa3b, v103
	v_mul_f32_e32 v99, 0xbfb8aa3b, v99
	v_exp_f32_e32 v100, v100
	v_exp_f32_e32 v96, v96
	v_exp_f32_e32 v101, v101
	v_exp_f32_e32 v97, v97
	v_exp_f32_e32 v102, v102
	v_exp_f32_e32 v98, v98
	v_exp_f32_e32 v103, v103
	v_exp_f32_e32 v99, v99
	v_add_f32_e32 v100, 1.0, v100
	v_add_f32_e32 v96, 1.0, v96
	v_add_f32_e32 v101, 1.0, v101
	v_add_f32_e32 v97, 1.0, v97
	v_add_f32_e32 v102, 1.0, v102
	v_add_f32_e32 v98, 1.0, v98
	v_add_f32_e32 v103, 1.0, v103
	v_add_f32_e32 v99, 1.0, v99
	v_rcp_f32_e32 v100, v100
	v_rcp_f32_e32 v96, v96
	v_rcp_f32_e32 v101, v101
	v_rcp_f32_e32 v97, v97
	v_rcp_f32_e32 v102, v102
	v_rcp_f32_e32 v98, v98
	v_rcp_f32_e32 v103, v103
	v_rcp_f32_e32 v99, v99
.LBB0_438:
	s_and_b64 vcc, exec, s[2:3]
	v_cvt_pk_bf16_f32 v100, v100, v101
	v_cvt_pk_bf16_f32 v101, v102, v103
	v_cvt_pk_bf16_f32 v102, v96, v97
	v_cvt_pk_bf16_f32 v103, v98, v99
	global_store_dwordx4 v[112:113], v[100:103], off offset:256 nt
	s_cbranch_vccnz .LBB0_440
	v_mul_f32_e32 v92, 0xbfb8aa3b, v92
	v_mul_f32_e32 v88, 0xbfb8aa3b, v88
	v_mul_f32_e32 v93, 0xbfb8aa3b, v93
	v_mul_f32_e32 v89, 0xbfb8aa3b, v89
	v_mul_f32_e32 v94, 0xbfb8aa3b, v94
	v_mul_f32_e32 v90, 0xbfb8aa3b, v90
	v_mul_f32_e32 v95, 0xbfb8aa3b, v95
	v_mul_f32_e32 v91, 0xbfb8aa3b, v91
	v_exp_f32_e32 v92, v92
	v_exp_f32_e32 v88, v88
	v_exp_f32_e32 v93, v93
	v_exp_f32_e32 v89, v89
	v_exp_f32_e32 v94, v94
	v_exp_f32_e32 v90, v90
	v_exp_f32_e32 v95, v95
	v_exp_f32_e32 v91, v91
	v_add_f32_e32 v92, 1.0, v92
	v_add_f32_e32 v88, 1.0, v88
	v_add_f32_e32 v93, 1.0, v93
	v_add_f32_e32 v89, 1.0, v89
	v_add_f32_e32 v94, 1.0, v94
	v_add_f32_e32 v90, 1.0, v90
	v_add_f32_e32 v95, 1.0, v95
	v_add_f32_e32 v91, 1.0, v91
	v_rcp_f32_e32 v92, v92
	v_rcp_f32_e32 v88, v88
	v_rcp_f32_e32 v93, v93
	v_rcp_f32_e32 v89, v89
	v_rcp_f32_e32 v94, v94
	v_rcp_f32_e32 v90, v90
	v_rcp_f32_e32 v95, v95
	v_rcp_f32_e32 v91, v91
; __device__ __forceinline__ unsigned cvt_pk_bf16(float lo, float hi) { unsigned r; asm volatile("v_cvt_pk_bf16_f32 %0, %1, %2" : "=v"(r) : "v"(lo), "v"(hi)); return r; }
; __device__ __forceinline__ float sigmoidf_(float x) { return __builtin_amdgcn_rcpf(1.0f + __builtin_amdgcn_exp2f(-1.4426950408889634f * x)); }
;     __device__ __forceinline__ void operator()(const Acc& acc, const Unit& u, int wr, int wc, int fr_, int fq_) const {
;     ...
;         if (hk == 0) {
; #pragma unroll
;             for (int ai = 0; ai < 2; ++ai)
; #pragma unroll
;                 for (int m = 0; m < 4; ++m) { bf16_t* rowp = base + (size_t)(row0 + ai * HALF + m * 16) * ld + col0;
; #pragma unroll
;                     for (int bj = 0; bj < 2; ++bj) { f32x4 v0 = acc[ai][bj][m][0], v1 = acc[ai][bj][m][1];
;                         if (sig) {
; #pragma unroll
;                             for (int j = 0; j < 4; ++j) { v0[j] = sigmoidf_(v0[j]); v1[j] = sigmoidf_(v1[j]); } }
;                         u32x4 w; w.x = cvt_pk_bf16(v0[0], v0[1]); w.y = cvt_pk_bf16(v0[2], v0[3]); w.z = cvt_pk_bf16(v1[0], v1[1]); w.w = cvt_pk_bf16(v1[2], v1[3]);
;                         *(u32x4*)(rowp + bj * HALF) = w; } }
;             return;
.LBB0_440:
	v_add_u32_e32 v96, 32, v132
	v_mad_i64_i32 v[96:97], s[0:1], s86, v96, 0
	v_lshl_add_u64 v[96:97], v[96:97], 1, v[128:129]
	s_and_b64 vcc, exec, s[2:3]
	v_cvt_pk_bf16_f32 v92, v92, v93
	v_cvt_pk_bf16_f32 v93, v94, v95
	v_cvt_pk_bf16_f32 v94, v88, v89
	v_cvt_pk_bf16_f32 v95, v90, v91
	global_store_dwordx4 v[96:97], v[92:95], off nt
	s_cbranch_vccnz .LBB0_442
	v_mul_f32_e32 v84, 0xbfb8aa3b, v84
	v_mul_f32_e32 v80, 0xbfb8aa3b, v80
	v_mul_f32_e32 v85, 0xbfb8aa3b, v85
	v_mul_f32_e32 v81, 0xbfb8aa3b, v81
	v_mul_f32_e32 v86, 0xbfb8aa3b, v86
	v_mul_f32_e32 v82, 0xbfb8aa3b, v82
	v_mul_f32_e32 v87, 0xbfb8aa3b, v87
	v_mul_f32_e32 v83, 0xbfb8aa3b, v83
	v_exp_f32_e32 v84, v84
	v_exp_f32_e32 v80, v80
	v_exp_f32_e32 v85, v85
	v_exp_f32_e32 v81, v81
	v_exp_f32_e32 v86, v86
	v_exp_f32_e32 v82, v82
	v_exp_f32_e32 v87, v87
	v_exp_f32_e32 v83, v83
	v_add_f32_e32 v84, 1.0, v84
	v_add_f32_e32 v80, 1.0, v80
	v_add_f32_e32 v85, 1.0, v85
	v_add_f32_e32 v81, 1.0, v81
	v_add_f32_e32 v86, 1.0, v86
	v_add_f32_e32 v82, 1.0, v82
	v_add_f32_e32 v87, 1.0, v87
	v_add_f32_e32 v83, 1.0, v83
	v_rcp_f32_e32 v84, v84
	v_rcp_f32_e32 v80, v80
	v_rcp_f32_e32 v85, v85
	v_rcp_f32_e32 v81, v81
	v_rcp_f32_e32 v86, v86
	v_rcp_f32_e32 v82, v82
	v_rcp_f32_e32 v87, v87
	v_rcp_f32_e32 v83, v83
.LBB0_442:
	s_and_b64 vcc, exec, s[2:3]
	v_cvt_pk_bf16_f32 v84, v84, v85
	v_cvt_pk_bf16_f32 v85, v86, v87
	v_cvt_pk_bf16_f32 v86, v80, v81
	v_cvt_pk_bf16_f32 v87, v82, v83
	global_store_dwordx4 v[96:97], v[84:87], off offset:256 nt
	s_cbranch_vccnz .LBB0_444
	v_mul_f32_e32 v76, 0xbfb8aa3b, v76
	v_mul_f32_e32 v72, 0xbfb8aa3b, v72
	v_mul_f32_e32 v77, 0xbfb8aa3b, v77
	v_mul_f32_e32 v73, 0xbfb8aa3b, v73
	v_mul_f32_e32 v78, 0xbfb8aa3b, v78
	v_mul_f32_e32 v74, 0xbfb8aa3b, v74
	v_mul_f32_e32 v79, 0xbfb8aa3b, v79
	v_mul_f32_e32 v75, 0xbfb8aa3b, v75
	v_exp_f32_e32 v76, v76
	v_exp_f32_e32 v72, v72
	v_exp_f32_e32 v77, v77
	v_exp_f32_e32 v73, v73
	v_exp_f32_e32 v78, v78
	v_exp_f32_e32 v74, v74
	v_exp_f32_e32 v79, v79
	v_exp_f32_e32 v75, v75
	v_add_f32_e32 v76, 1.0, v76
	v_add_f32_e32 v72, 1.0, v72
	v_add_f32_e32 v77, 1.0, v77
	v_add_f32_e32 v73, 1.0, v73
	v_add_f32_e32 v78, 1.0, v78
	v_add_f32_e32 v74, 1.0, v74
	v_add_f32_e32 v79, 1.0, v79
	v_add_f32_e32 v75, 1.0, v75
	v_rcp_f32_e32 v76, v76
	v_rcp_f32_e32 v72, v72
	v_rcp_f32_e32 v77, v77
	v_rcp_f32_e32 v73, v73
	v_rcp_f32_e32 v78, v78
	v_rcp_f32_e32 v74, v74
	v_rcp_f32_e32 v79, v79
	v_rcp_f32_e32 v75, v75
.LBB0_444:
	v_add_u32_e32 v80, 48, v132
	v_mad_i64_i32 v[80:81], s[0:1], s86, v80, 0
	v_lshl_add_u64 v[80:81], v[80:81], 1, v[128:129]
	s_and_b64 vcc, exec, s[2:3]
	v_cvt_pk_bf16_f32 v76, v76, v77
	v_cvt_pk_bf16_f32 v77, v78, v79
	v_cvt_pk_bf16_f32 v78, v72, v73
	v_cvt_pk_bf16_f32 v79, v74, v75
	global_store_dwordx4 v[80:81], v[76:79], off nt
	s_cbranch_vccnz .LBB0_446
	v_mul_f32_e32 v68, 0xbfb8aa3b, v68
	v_mul_f32_e32 v64, 0xbfb8aa3b, v64
	v_mul_f32_e32 v69, 0xbfb8aa3b, v69
	v_mul_f32_e32 v65, 0xbfb8aa3b, v65
	v_mul_f32_e32 v70, 0xbfb8aa3b, v70
	v_mul_f32_e32 v66, 0xbfb8aa3b, v66
	v_mul_f32_e32 v71, 0xbfb8aa3b, v71
	v_mul_f32_e32 v67, 0xbfb8aa3b, v67
	v_exp_f32_e32 v68, v68
	v_exp_f32_e32 v64, v64
	v_exp_f32_e32 v69, v69
	v_exp_f32_e32 v65, v65
	v_exp_f32_e32 v70, v70
	v_exp_f32_e32 v66, v66
	v_exp_f32_e32 v71, v71
	v_exp_f32_e32 v67, v67
	v_add_f32_e32 v68, 1.0, v68
	v_add_f32_e32 v64, 1.0, v64
	v_add_f32_e32 v69, 1.0, v69
	v_add_f32_e32 v65, 1.0, v65
	v_add_f32_e32 v70, 1.0, v70
	v_add_f32_e32 v66, 1.0, v66
	v_add_f32_e32 v71, 1.0, v71
	v_add_f32_e32 v67, 1.0, v67
	v_rcp_f32_e32 v68, v68
	v_rcp_f32_e32 v64, v64
	v_rcp_f32_e32 v69, v69
	v_rcp_f32_e32 v65, v65
	v_rcp_f32_e32 v70, v70
	v_rcp_f32_e32 v66, v66
	v_rcp_f32_e32 v71, v71
	v_rcp_f32_e32 v67, v67
.LBB0_446:
	s_and_b64 vcc, exec, s[2:3]
	v_cvt_pk_bf16_f32 v68, v68, v69
	v_cvt_pk_bf16_f32 v69, v70, v71
	v_cvt_pk_bf16_f32 v70, v64, v65
	v_cvt_pk_bf16_f32 v71, v66, v67
	global_store_dwordx4 v[80:81], v[68:71], off offset:256 nt
	s_cbranch_vccnz .LBB0_448
	v_mul_f32_e32 v60, 0xbfb8aa3b, v60
	v_mul_f32_e32 v56, 0xbfb8aa3b, v56
	v_mul_f32_e32 v61, 0xbfb8aa3b, v61
	v_mul_f32_e32 v57, 0xbfb8aa3b, v57
	v_mul_f32_e32 v62, 0xbfb8aa3b, v62
	v_mul_f32_e32 v58, 0xbfb8aa3b, v58
	v_mul_f32_e32 v63, 0xbfb8aa3b, v63
	v_mul_f32_e32 v59, 0xbfb8aa3b, v59
	v_exp_f32_e32 v60, v60
	v_exp_f32_e32 v56, v56
	v_exp_f32_e32 v61, v61
	v_exp_f32_e32 v57, v57
	v_exp_f32_e32 v62, v62
	v_exp_f32_e32 v58, v58
	v_exp_f32_e32 v63, v63
	v_exp_f32_e32 v59, v59
	v_add_f32_e32 v60, 1.0, v60
	v_add_f32_e32 v56, 1.0, v56
	v_add_f32_e32 v61, 1.0, v61
	v_add_f32_e32 v57, 1.0, v57
	v_add_f32_e32 v62, 1.0, v62
	v_add_f32_e32 v58, 1.0, v58
	v_add_f32_e32 v63, 1.0, v63
	v_add_f32_e32 v59, 1.0, v59
	v_rcp_f32_e32 v60, v60
	v_rcp_f32_e32 v56, v56
	v_rcp_f32_e32 v61, v61
	v_rcp_f32_e32 v57, v57
	v_rcp_f32_e32 v62, v62
	v_rcp_f32_e32 v58, v58
	v_rcp_f32_e32 v63, v63
	v_rcp_f32_e32 v59, v59
.LBB0_448:
	v_add_u32_e32 v64, 0x80, v132
	v_mad_i64_i32 v[64:65], s[0:1], s86, v64, 0
	v_lshl_add_u64 v[64:65], v[64:65], 1, v[128:129]
	s_and_b64 vcc, exec, s[2:3]
	v_cvt_pk_bf16_f32 v60, v60, v61
	v_cvt_pk_bf16_f32 v61, v62, v63
	v_cvt_pk_bf16_f32 v62, v56, v57
	v_cvt_pk_bf16_f32 v63, v58, v59
	global_store_dwordx4 v[64:65], v[60:63], off nt
	s_cbranch_vccnz .LBB0_450
	v_mul_f32_e32 v52, 0xbfb8aa3b, v52
	v_mul_f32_e32 v48, 0xbfb8aa3b, v48
	v_mul_f32_e32 v53, 0xbfb8aa3b, v53
	v_mul_f32_e32 v49, 0xbfb8aa3b, v49
	v_mul_f32_e32 v54, 0xbfb8aa3b, v54
	v_mul_f32_e32 v50, 0xbfb8aa3b, v50
	v_mul_f32_e32 v55, 0xbfb8aa3b, v55
	v_mul_f32_e32 v51, 0xbfb8aa3b, v51
	v_exp_f32_e32 v52, v52
	v_exp_f32_e32 v48, v48
	v_exp_f32_e32 v53, v53
	v_exp_f32_e32 v49, v49
	v_exp_f32_e32 v54, v54
	v_exp_f32_e32 v50, v50
	v_exp_f32_e32 v55, v55
	v_exp_f32_e32 v51, v51
	v_add_f32_e32 v52, 1.0, v52
	v_add_f32_e32 v48, 1.0, v48
	v_add_f32_e32 v53, 1.0, v53
	v_add_f32_e32 v49, 1.0, v49
	v_add_f32_e32 v54, 1.0, v54
	v_add_f32_e32 v50, 1.0, v50
	v_add_f32_e32 v55, 1.0, v55
	v_add_f32_e32 v51, 1.0, v51
	v_rcp_f32_e32 v52, v52
	v_rcp_f32_e32 v48, v48
	v_rcp_f32_e32 v53, v53
	v_rcp_f32_e32 v49, v49
	v_rcp_f32_e32 v54, v54
	v_rcp_f32_e32 v50, v50
	v_rcp_f32_e32 v55, v55
	v_rcp_f32_e32 v51, v51
; __device__ __forceinline__ unsigned cvt_pk_bf16(float lo, float hi) { unsigned r; asm volatile("v_cvt_pk_bf16_f32 %0, %1, %2" : "=v"(r) : "v"(lo), "v"(hi)); return r; }
; __device__ __forceinline__ float sigmoidf_(float x) { return __builtin_amdgcn_rcpf(1.0f + __builtin_amdgcn_exp2f(-1.4426950408889634f * x)); }
;     __device__ __forceinline__ void operator()(const Acc& acc, const Unit& u, int wr, int wc, int fr_, int fq_) const {
;     ...
;         if (hk == 0) {
; #pragma unroll
;             for (int ai = 0; ai < 2; ++ai)
; #pragma unroll
;                 for (int m = 0; m < 4; ++m) { bf16_t* rowp = base + (size_t)(row0 + ai * HALF + m * 16) * ld + col0;
; #pragma unroll
;                     for (int bj = 0; bj < 2; ++bj) { f32x4 v0 = acc[ai][bj][m][0], v1 = acc[ai][bj][m][1];
;                         if (sig) {
; #pragma unroll
;                             for (int j = 0; j < 4; ++j) { v0[j] = sigmoidf_(v0[j]); v1[j] = sigmoidf_(v1[j]); } }
;                         u32x4 w; w.x = cvt_pk_bf16(v0[0], v0[1]); w.y = cvt_pk_bf16(v0[2], v0[3]); w.z = cvt_pk_bf16(v1[0], v1[1]); w.w = cvt_pk_bf16(v1[2], v1[3]);
;                         *(u32x4*)(rowp + bj * HALF) = w; } }
;             return;
.LBB0_450:
	s_and_b64 vcc, exec, s[2:3]
	v_cvt_pk_bf16_f32 v52, v52, v53
	v_cvt_pk_bf16_f32 v53, v54, v55
	v_cvt_pk_bf16_f32 v54, v48, v49
	v_cvt_pk_bf16_f32 v55, v50, v51
	global_store_dwordx4 v[64:65], v[52:55], off offset:256 nt
	s_cbranch_vccnz .LBB0_452
	v_mul_f32_e32 v44, 0xbfb8aa3b, v44
	v_mul_f32_e32 v40, 0xbfb8aa3b, v40
	v_mul_f32_e32 v45, 0xbfb8aa3b, v45
	v_mul_f32_e32 v41, 0xbfb8aa3b, v41
	v_mul_f32_e32 v46, 0xbfb8aa3b, v46
	v_mul_f32_e32 v42, 0xbfb8aa3b, v42
	v_mul_f32_e32 v47, 0xbfb8aa3b, v47
	v_mul_f32_e32 v43, 0xbfb8aa3b, v43
	v_exp_f32_e32 v44, v44
	v_exp_f32_e32 v40, v40
	v_exp_f32_e32 v45, v45
	v_exp_f32_e32 v41, v41
	v_exp_f32_e32 v46, v46
	v_exp_f32_e32 v42, v42
	v_exp_f32_e32 v47, v47
	v_exp_f32_e32 v43, v43
	v_add_f32_e32 v44, 1.0, v44
	v_add_f32_e32 v40, 1.0, v40
	v_add_f32_e32 v45, 1.0, v45
	v_add_f32_e32 v41, 1.0, v41
	v_add_f32_e32 v46, 1.0, v46
	v_add_f32_e32 v42, 1.0, v42
	v_add_f32_e32 v47, 1.0, v47
	v_add_f32_e32 v43, 1.0, v43
	v_rcp_f32_e32 v44, v44
	v_rcp_f32_e32 v40, v40
	v_rcp_f32_e32 v45, v45
	v_rcp_f32_e32 v41, v41
	v_rcp_f32_e32 v46, v46
	v_rcp_f32_e32 v42, v42
	v_rcp_f32_e32 v47, v47
	v_rcp_f32_e32 v43, v43
.LBB0_452:
	v_add_u32_e32 v48, 0x90, v132
	v_mad_i64_i32 v[48:49], s[0:1], s86, v48, 0
	v_lshl_add_u64 v[48:49], v[48:49], 1, v[128:129]
	s_and_b64 vcc, exec, s[2:3]
	v_cvt_pk_bf16_f32 v44, v44, v45
	v_cvt_pk_bf16_f32 v45, v46, v47
	v_cvt_pk_bf16_f32 v46, v40, v41
	v_cvt_pk_bf16_f32 v47, v42, v43
	global_store_dwordx4 v[48:49], v[44:47], off nt
	s_cbranch_vccnz .LBB0_454
	v_mul_f32_e32 v36, 0xbfb8aa3b, v36
	v_mul_f32_e32 v32, 0xbfb8aa3b, v32
	v_mul_f32_e32 v37, 0xbfb8aa3b, v37
	v_mul_f32_e32 v33, 0xbfb8aa3b, v33
	v_mul_f32_e32 v38, 0xbfb8aa3b, v38
	v_mul_f32_e32 v34, 0xbfb8aa3b, v34
	v_mul_f32_e32 v39, 0xbfb8aa3b, v39
	v_mul_f32_e32 v35, 0xbfb8aa3b, v35
	v_exp_f32_e32 v36, v36
	v_exp_f32_e32 v32, v32
	v_exp_f32_e32 v37, v37
	v_exp_f32_e32 v33, v33
	v_exp_f32_e32 v38, v38
	v_exp_f32_e32 v34, v34
	v_exp_f32_e32 v39, v39
	v_exp_f32_e32 v35, v35
	v_add_f32_e32 v36, 1.0, v36
	v_add_f32_e32 v32, 1.0, v32
	v_add_f32_e32 v37, 1.0, v37
	v_add_f32_e32 v33, 1.0, v33
	v_add_f32_e32 v38, 1.0, v38
	v_add_f32_e32 v34, 1.0, v34
	v_add_f32_e32 v39, 1.0, v39
	v_add_f32_e32 v35, 1.0, v35
	v_rcp_f32_e32 v36, v36
	v_rcp_f32_e32 v32, v32
	v_rcp_f32_e32 v37, v37
	v_rcp_f32_e32 v33, v33
	v_rcp_f32_e32 v38, v38
	v_rcp_f32_e32 v34, v34
	v_rcp_f32_e32 v39, v39
	v_rcp_f32_e32 v35, v35
.LBB0_454:
	s_and_b64 vcc, exec, s[2:3]
	v_cvt_pk_bf16_f32 v36, v36, v37
	v_cvt_pk_bf16_f32 v37, v38, v39
	v_cvt_pk_bf16_f32 v38, v32, v33
	v_cvt_pk_bf16_f32 v39, v34, v35
	global_store_dwordx4 v[48:49], v[36:39], off offset:256 nt
	s_cbranch_vccnz .LBB0_456
	v_mul_f32_e32 v28, 0xbfb8aa3b, v28
	v_mul_f32_e32 v24, 0xbfb8aa3b, v24
	v_mul_f32_e32 v29, 0xbfb8aa3b, v29
	v_mul_f32_e32 v25, 0xbfb8aa3b, v25
	v_mul_f32_e32 v30, 0xbfb8aa3b, v30
	v_mul_f32_e32 v26, 0xbfb8aa3b, v26
	v_mul_f32_e32 v31, 0xbfb8aa3b, v31
	v_mul_f32_e32 v27, 0xbfb8aa3b, v27
	v_exp_f32_e32 v28, v28
	v_exp_f32_e32 v24, v24
	v_exp_f32_e32 v29, v29
	v_exp_f32_e32 v25, v25
	v_exp_f32_e32 v30, v30
	v_exp_f32_e32 v26, v26
	v_exp_f32_e32 v31, v31
	v_exp_f32_e32 v27, v27
	v_add_f32_e32 v28, 1.0, v28
	v_add_f32_e32 v24, 1.0, v24
	v_add_f32_e32 v29, 1.0, v29
	v_add_f32_e32 v25, 1.0, v25
	v_add_f32_e32 v30, 1.0, v30
	v_add_f32_e32 v26, 1.0, v26
	v_add_f32_e32 v31, 1.0, v31
	v_add_f32_e32 v27, 1.0, v27
	v_rcp_f32_e32 v28, v28
	v_rcp_f32_e32 v24, v24
	v_rcp_f32_e32 v29, v29
	v_rcp_f32_e32 v25, v25
	v_rcp_f32_e32 v30, v30
	v_rcp_f32_e32 v26, v26
	v_rcp_f32_e32 v31, v31
	v_rcp_f32_e32 v27, v27
; __device__ __forceinline__ unsigned cvt_pk_bf16(float lo, float hi) { unsigned r; asm volatile("v_cvt_pk_bf16_f32 %0, %1, %2" : "=v"(r) : "v"(lo), "v"(hi)); return r; }
; __device__ __forceinline__ float sigmoidf_(float x) { return __builtin_amdgcn_rcpf(1.0f + __builtin_amdgcn_exp2f(-1.4426950408889634f * x)); }
;     __device__ __forceinline__ void operator()(const Acc& acc, const Unit& u, int wr, int wc, int fr_, int fq_) const {
;     ...
;         if (hk == 0) {
; #pragma unroll
;             for (int ai = 0; ai < 2; ++ai)
; #pragma unroll
;                 for (int m = 0; m < 4; ++m) { bf16_t* rowp = base + (size_t)(row0 + ai * HALF + m * 16) * ld + col0;
; #pragma unroll
;                     for (int bj = 0; bj < 2; ++bj) { f32x4 v0 = acc[ai][bj][m][0], v1 = acc[ai][bj][m][1];
;                         if (sig) {
; #pragma unroll
;                             for (int j = 0; j < 4; ++j) { v0[j] = sigmoidf_(v0[j]); v1[j] = sigmoidf_(v1[j]); } }
;                         u32x4 w; w.x = cvt_pk_bf16(v0[0], v0[1]); w.y = cvt_pk_bf16(v0[2], v0[3]); w.z = cvt_pk_bf16(v1[0], v1[1]); w.w = cvt_pk_bf16(v1[2], v1[3]);
;                         *(u32x4*)(rowp + bj * HALF) = w; } }
;             return;
.LBB0_456:
	v_add_u32_e32 v32, 0xa0, v132
	v_mad_i64_i32 v[32:33], s[0:1], s86, v32, 0
	v_lshl_add_u64 v[32:33], v[32:33], 1, v[128:129]
	s_and_b64 vcc, exec, s[2:3]
	v_cvt_pk_bf16_f32 v28, v28, v29
	v_cvt_pk_bf16_f32 v29, v30, v31
	v_cvt_pk_bf16_f32 v30, v24, v25
	v_cvt_pk_bf16_f32 v31, v26, v27
	global_store_dwordx4 v[32:33], v[28:31], off nt
	s_cbranch_vccnz .LBB0_458
	v_mul_f32_e32 v20, 0xbfb8aa3b, v20
	v_mul_f32_e32 v16, 0xbfb8aa3b, v16
	v_mul_f32_e32 v21, 0xbfb8aa3b, v21
	v_mul_f32_e32 v17, 0xbfb8aa3b, v17
	v_mul_f32_e32 v22, 0xbfb8aa3b, v22
	v_mul_f32_e32 v18, 0xbfb8aa3b, v18
	v_mul_f32_e32 v23, 0xbfb8aa3b, v23
	v_mul_f32_e32 v19, 0xbfb8aa3b, v19
	v_exp_f32_e32 v20, v20
	v_exp_f32_e32 v16, v16
	v_exp_f32_e32 v21, v21
	v_exp_f32_e32 v17, v17
	v_exp_f32_e32 v22, v22
	v_exp_f32_e32 v18, v18
	v_exp_f32_e32 v23, v23
	v_exp_f32_e32 v19, v19
	v_add_f32_e32 v20, 1.0, v20
	v_add_f32_e32 v16, 1.0, v16
	v_add_f32_e32 v21, 1.0, v21
	v_add_f32_e32 v17, 1.0, v17
	v_add_f32_e32 v22, 1.0, v22
	v_add_f32_e32 v18, 1.0, v18
	v_add_f32_e32 v23, 1.0, v23
	v_add_f32_e32 v19, 1.0, v19
	v_rcp_f32_e32 v20, v20
	v_rcp_f32_e32 v16, v16
	v_rcp_f32_e32 v21, v21
	v_rcp_f32_e32 v17, v17
	v_rcp_f32_e32 v22, v22
	v_rcp_f32_e32 v18, v18
	v_rcp_f32_e32 v23, v23
	v_rcp_f32_e32 v19, v19
.LBB0_458:
	s_and_b64 vcc, exec, s[2:3]
	v_cvt_pk_bf16_f32 v20, v20, v21
	v_cvt_pk_bf16_f32 v21, v22, v23
	v_cvt_pk_bf16_f32 v22, v16, v17
	v_cvt_pk_bf16_f32 v23, v18, v19
	global_store_dwordx4 v[32:33], v[20:23], off offset:256 nt
	s_cbranch_vccnz .LBB0_460
	v_mul_f32_e32 v12, 0xbfb8aa3b, v12
	v_mul_f32_e32 v8, 0xbfb8aa3b, v8
	v_mul_f32_e32 v13, 0xbfb8aa3b, v13
	v_mul_f32_e32 v9, 0xbfb8aa3b, v9
	v_mul_f32_e32 v14, 0xbfb8aa3b, v14
	v_mul_f32_e32 v10, 0xbfb8aa3b, v10
	v_mul_f32_e32 v15, 0xbfb8aa3b, v15
	v_mul_f32_e32 v11, 0xbfb8aa3b, v11
	v_exp_f32_e32 v12, v12
	v_exp_f32_e32 v8, v8
	v_exp_f32_e32 v13, v13
	v_exp_f32_e32 v9, v9
	v_exp_f32_e32 v14, v14
	v_exp_f32_e32 v10, v10
	v_exp_f32_e32 v15, v15
	v_exp_f32_e32 v11, v11
	v_add_f32_e32 v12, 1.0, v12
	v_add_f32_e32 v8, 1.0, v8
	v_add_f32_e32 v13, 1.0, v13
	v_add_f32_e32 v9, 1.0, v9
	v_add_f32_e32 v14, 1.0, v14
	v_add_f32_e32 v10, 1.0, v10
	v_add_f32_e32 v15, 1.0, v15
	v_add_f32_e32 v11, 1.0, v11
	v_rcp_f32_e32 v12, v12
	v_rcp_f32_e32 v8, v8
	v_rcp_f32_e32 v13, v13
	v_rcp_f32_e32 v9, v9
	v_rcp_f32_e32 v14, v14
	v_rcp_f32_e32 v10, v10
	v_rcp_f32_e32 v15, v15
	v_rcp_f32_e32 v11, v11
.LBB0_460:
	v_add_u32_e32 v16, 0xb0, v132
	v_mad_i64_i32 v[16:17], s[0:1], s86, v16, 0
	v_lshl_add_u64 v[16:17], v[16:17], 1, v[128:129]
	s_and_b64 vcc, exec, s[2:3]
	v_cvt_pk_bf16_f32 v12, v12, v13
	v_cvt_pk_bf16_f32 v13, v14, v15
	v_cvt_pk_bf16_f32 v14, v8, v9
	v_cvt_pk_bf16_f32 v15, v10, v11
	global_store_dwordx4 v[16:17], v[12:15], off nt
	s_cbranch_vccnz .LBB0_462
	v_mul_f32_e32 v4, 0xbfb8aa3b, v4
	v_mul_f32_e32 v0, 0xbfb8aa3b, v0
	v_mul_f32_e32 v5, 0xbfb8aa3b, v5
	v_mul_f32_e32 v1, 0xbfb8aa3b, v1
	v_mul_f32_e32 v6, 0xbfb8aa3b, v6
	v_mul_f32_e32 v2, 0xbfb8aa3b, v2
	v_mul_f32_e32 v7, 0xbfb8aa3b, v7
	v_mul_f32_e32 v3, 0xbfb8aa3b, v3
	v_exp_f32_e32 v4, v4
	v_exp_f32_e32 v0, v0
	v_exp_f32_e32 v5, v5
	v_exp_f32_e32 v1, v1
	v_exp_f32_e32 v6, v6
	v_exp_f32_e32 v2, v2
	v_exp_f32_e32 v7, v7
	v_exp_f32_e32 v3, v3
	v_add_f32_e32 v4, 1.0, v4
	v_add_f32_e32 v0, 1.0, v0
	v_add_f32_e32 v5, 1.0, v5
	v_add_f32_e32 v1, 1.0, v1
	v_add_f32_e32 v6, 1.0, v6
	v_add_f32_e32 v2, 1.0, v2
	v_add_f32_e32 v7, 1.0, v7
	v_add_f32_e32 v3, 1.0, v3
	v_rcp_f32_e32 v4, v4
	v_rcp_f32_e32 v0, v0
	v_rcp_f32_e32 v5, v5
	v_rcp_f32_e32 v1, v1
	v_rcp_f32_e32 v6, v6
	v_rcp_f32_e32 v2, v2
	v_rcp_f32_e32 v7, v7
	v_rcp_f32_e32 v3, v3
.LBB0_462:
	v_cvt_pk_bf16_f32 v4, v4, v5
	v_cvt_pk_bf16_f32 v5, v6, v7
	v_cvt_pk_bf16_f32 v6, v0, v1
	v_cvt_pk_bf16_f32 v7, v2, v3
	global_store_dwordx4 v[16:17], v[4:7], off offset:256 nt

; __device__ __forceinline__ float sigmoidf_(float x) { return __builtin_amdgcn_rcpf(1.0f + __builtin_amdgcn_exp2f(-1.4426950408889634f * x)); }
;     __device__ __forceinline__ void operator()(const Acc& acc, const Unit& u, int wr, int wc, int fr, int fq) const {
;         const int row0 = u.pm * BM + wr * 64 + fr, col0 = u.pn * HALF + wc * 32 + 8 * fq;
; #pragma unroll
;         for (int ai = 0; ai < 2; ++ai)
; #pragma unroll
;             for (int m = 0; m < 4; ++m) { float o[8];
; #pragma unroll
;                 for (int n = 0; n < 2; ++n)
; #pragma unroll
;                     for (int j = 0; j < 4; ++j) { const float gg = acc[ai][0][m][n][j], uu = acc[ai][1][m][n][j]; o[4 * n + j] = gg * sigmoidf_(gg) * uu; }
;                 *(u32x4*)(HM + (size_t)(row0 + ai * HALF + m * 16) * DFF + col0) = pack8(o); }
;     }
.LBB0_972:
	v_mul_f32_e32 v151, 0xbfb8aa3b, v124
	v_exp_f32_e32 v151, v151
	v_mul_f32_e32 v152, 0xbfb8aa3b, v125
	v_exp_f32_e32 v153, v152
	v_lshl_or_b32 v152, s44, 7, v146
	v_add_f32_e32 v151, 1.0, v151
	v_rcp_f32_e32 v151, v151
	v_add_f32_e32 v153, 1.0, v153
	v_rcp_f32_e32 v154, v153
	v_lshl_add_u32 v150, s24, 8, v144
	v_mul_f32_e32 v124, v124, v151
	v_mul_f32_e32 v116, v124, v116
	v_mul_f32_e32 v124, v125, v154
	v_mul_f32_e32 v125, 0xbfb8aa3b, v126
	v_exp_f32_e32 v125, v125
	v_mul_f32_e32 v151, 0xbfb8aa3b, v127
	v_exp_f32_e32 v151, v151
	v_mul_f32_e32 v117, v124, v117
	v_add_f32_e32 v124, 1.0, v125
	v_rcp_f32_e32 v124, v124
	v_add_f32_e32 v125, 1.0, v151
	v_mul_f32_e32 v151, 0xbfb8aa3b, v120
	v_rcp_f32_e32 v125, v125
	v_exp_f32_e32 v151, v151
	v_mul_f32_e32 v124, v126, v124
	v_mul_f32_e32 v118, v124, v118
	v_mul_f32_e32 v124, v127, v125
	v_add_f32_e32 v125, 1.0, v151
	v_rcp_f32_e32 v125, v125
	v_mul_f32_e32 v126, 0xbfb8aa3b, v121
	v_exp_f32_e32 v126, v126
	v_mul_f32_e32 v119, v124, v119
	v_mul_f32_e32 v120, v120, v125
	v_mul_f32_e32 v112, v120, v112
	v_add_f32_e32 v120, 1.0, v126
	v_mul_f32_e32 v124, 0xbfb8aa3b, v122
	v_rcp_f32_e32 v120, v120
	v_exp_f32_e32 v124, v124
	v_mul_f32_e32 v125, 0xbfb8aa3b, v123
	v_exp_f32_e32 v125, v125
	v_mul_f32_e32 v120, v121, v120
	v_add_f32_e32 v121, 1.0, v124
	v_rcp_f32_e32 v121, v121
	v_add_f32_e32 v124, 1.0, v125
	v_rcp_f32_e32 v124, v124
	v_mul_f32_e32 v113, v120, v113
	v_mul_f32_e32 v120, v122, v121
	v_mul_f32_e32 v122, 0xbfb8aa3b, v108
	v_mul_f32_e32 v114, v120, v114
	v_mul_f32_e32 v120, v123, v124
	v_exp_f32_e32 v122, v122
	v_mul_f32_e32 v123, 0xbfb8aa3b, v109
	v_exp_f32_e32 v123, v123
	v_ashrrev_i32_e32 v153, 31, v152
	v_add_f32_e32 v122, 1.0, v122
	v_rcp_f32_e32 v122, v122
	v_add_f32_e32 v123, 1.0, v123
	v_rcp_f32_e32 v123, v123
	v_mul_f32_e32 v115, v120, v115
	v_cvt_pk_bf16_f32 v116, v116, v117
	v_cvt_pk_bf16_f32 v117, v118, v119
	v_cvt_pk_bf16_f32 v118, v112, v113
	v_mov_b64_e32 v[112:113], s[12:13]
	v_cvt_pk_bf16_f32 v119, v114, v115
	v_mad_i64_i32 v[120:121], s[0:1], v150, s43, v[112:113]
	v_lshlrev_b64 v[114:115], 1, v[152:153]
	v_mul_f32_e32 v108, v108, v122
	v_lshl_add_u64 v[120:121], v[120:121], 0, v[114:115]
	v_mul_f32_e32 v100, v108, v100
	v_mul_f32_e32 v108, v109, v123
	v_mul_f32_e32 v109, 0xbfb8aa3b, v110
	global_store_dwordx4 v[120:121], v[116:119], off nt
	v_exp_f32_e32 v109, v109
	v_mul_f32_e32 v101, v108, v101
	v_mul_f32_e32 v116, 0xbfb8aa3b, v111
	v_exp_f32_e32 v116, v116
	v_add_f32_e32 v108, 1.0, v109
	v_rcp_f32_e32 v108, v108
	s_andn2_b64 vcc, exec, s[2:3]
	v_add_f32_e32 v109, 1.0, v116
	v_mul_f32_e32 v116, 0xbfb8aa3b, v104
	v_rcp_f32_e32 v109, v109
	v_exp_f32_e32 v116, v116
	v_mul_f32_e32 v108, v110, v108
	v_mul_f32_e32 v102, v108, v102
	v_mul_f32_e32 v108, v111, v109
	v_add_f32_e32 v109, 1.0, v116
	v_rcp_f32_e32 v109, v109
	v_mul_f32_e32 v110, 0xbfb8aa3b, v105
	v_exp_f32_e32 v110, v110
	v_mul_f32_e32 v103, v108, v103
	v_mul_f32_e32 v104, v104, v109
	v_mul_f32_e32 v104, v104, v96
	v_add_f32_e32 v96, 1.0, v110
	v_mul_f32_e32 v108, 0xbfb8aa3b, v106
	v_rcp_f32_e32 v96, v96
	v_exp_f32_e32 v108, v108
	v_mul_f32_e32 v109, 0xbfb8aa3b, v107
	v_exp_f32_e32 v109, v109
	v_mul_f32_e32 v96, v105, v96
	v_add_f32_e32 v105, 1.0, v108
	v_rcp_f32_e32 v105, v105
	v_add_f32_e32 v108, 1.0, v109
	v_rcp_f32_e32 v108, v108
	v_mul_f32_e32 v109, v96, v97
	v_mul_f32_e32 v96, v106, v105
	v_mul_f32_e32 v105, v96, v98
	v_mul_f32_e32 v96, v107, v108
	v_mul_f32_e32 v99, v96, v99
	v_cvt_pk_bf16_f32 v96, v100, v101
	v_cvt_pk_bf16_f32 v97, v102, v103
	v_mul_f32_e32 v102, 0xbfb8aa3b, v92
	v_exp_f32_e32 v102, v102
	v_mul_f32_e32 v103, 0xbfb8aa3b, v93
	v_exp_f32_e32 v103, v103
	v_or_b32_e32 v100, 16, v150
	v_add_f32_e32 v102, 1.0, v102
	v_rcp_f32_e32 v102, v102
	v_add_f32_e32 v103, 1.0, v103
	v_rcp_f32_e32 v103, v103
	v_mad_i64_i32 v[100:101], s[0:1], v100, s43, v[112:113]
	v_mul_f32_e32 v92, v92, v102
	v_lshl_add_u64 v[100:101], v[100:101], 0, v[114:115]
	v_mul_f32_e32 v84, v92, v84
	v_mul_f32_e32 v92, v93, v103
	v_mul_f32_e32 v93, 0xbfb8aa3b, v94
	v_cvt_pk_bf16_f32 v98, v104, v109
	v_cvt_pk_bf16_f32 v99, v105, v99
	global_store_dwordx4 v[100:101], v[96:99], off nt
	v_exp_f32_e32 v93, v93
	v_mul_f32_e32 v85, v92, v85
	v_mul_f32_e32 v96, 0xbfb8aa3b, v95
	v_exp_f32_e32 v96, v96
	v_add_f32_e32 v92, 1.0, v93
	v_rcp_f32_e32 v92, v92
	v_add_f32_e32 v93, 1.0, v96
	v_mul_f32_e32 v96, 0xbfb8aa3b, v88
	v_rcp_f32_e32 v93, v93
	v_exp_f32_e32 v96, v96
	v_mul_f32_e32 v92, v94, v92
	v_mul_f32_e32 v86, v92, v86
	v_mul_f32_e32 v92, v95, v93
	v_add_f32_e32 v93, 1.0, v96
	v_rcp_f32_e32 v93, v93
	v_mul_f32_e32 v94, 0xbfb8aa3b, v89
	v_exp_f32_e32 v94, v94
	v_mul_f32_e32 v87, v92, v87
	v_mul_f32_e32 v88, v88, v93
	v_mul_f32_e32 v88, v88, v80
	v_add_f32_e32 v80, 1.0, v94
	v_mul_f32_e32 v92, 0xbfb8aa3b, v90
	v_rcp_f32_e32 v80, v80
	v_exp_f32_e32 v92, v92
	v_mul_f32_e32 v93, 0xbfb8aa3b, v91
	v_exp_f32_e32 v93, v93
	v_mul_f32_e32 v80, v89, v80
	v_add_f32_e32 v89, 1.0, v92
	v_rcp_f32_e32 v89, v89
	v_add_f32_e32 v92, 1.0, v93
	v_rcp_f32_e32 v92, v92
	v_mul_f32_e32 v93, v80, v81
	v_mul_f32_e32 v80, v90, v89
	v_mul_f32_e32 v89, v80, v82
	v_mul_f32_e32 v80, v91, v92
	v_mul_f32_e32 v83, v80, v83
	v_cvt_pk_bf16_f32 v80, v84, v85
	v_cvt_pk_bf16_f32 v81, v86, v87
	v_mul_f32_e32 v86, 0xbfb8aa3b, v76
	v_exp_f32_e32 v86, v86
	v_mul_f32_e32 v87, 0xbfb8aa3b, v77
	v_exp_f32_e32 v87, v87
	v_or_b32_e32 v84, 32, v150
	v_add_f32_e32 v86, 1.0, v86
	v_rcp_f32_e32 v86, v86
	v_add_f32_e32 v87, 1.0, v87
	v_rcp_f32_e32 v87, v87
	v_mad_i64_i32 v[84:85], s[0:1], v84, s43, v[112:113]
	v_mul_f32_e32 v76, v76, v86
	v_lshl_add_u64 v[84:85], v[84:85], 0, v[114:115]
; __device__ __forceinline__ float sigmoidf_(float x) { return __builtin_amdgcn_rcpf(1.0f + __builtin_amdgcn_exp2f(-1.4426950408889634f * x)); }
;     __device__ __forceinline__ void operator()(const Acc& acc, const Unit& u, int wr, int wc, int fr, int fq) const {
;         const int row0 = u.pm * BM + wr * 64 + fr, col0 = u.pn * HALF + wc * 32 + 8 * fq;
; #pragma unroll
;         for (int ai = 0; ai < 2; ++ai)
; #pragma unroll
;             for (int m = 0; m < 4; ++m) { float o[8];
; #pragma unroll
;                 for (int n = 0; n < 2; ++n)
; #pragma unroll
;                     for (int j = 0; j < 4; ++j) { const float gg = acc[ai][0][m][n][j], uu = acc[ai][1][m][n][j]; o[4 * n + j] = gg * sigmoidf_(gg) * uu; }
;                 *(u32x4*)(HM + (size_t)(row0 + ai * HALF + m * 16) * DFF + col0) = pack8(o); }
;     }
	v_mul_f32_e32 v68, v76, v68
	v_mul_f32_e32 v76, v77, v87
	v_mul_f32_e32 v77, 0xbfb8aa3b, v78
	v_cvt_pk_bf16_f32 v82, v88, v93
	v_cvt_pk_bf16_f32 v83, v89, v83
	global_store_dwordx4 v[84:85], v[80:83], off nt
	v_exp_f32_e32 v77, v77
	v_mul_f32_e32 v69, v76, v69
	v_mul_f32_e32 v80, 0xbfb8aa3b, v79
	v_exp_f32_e32 v80, v80
	v_add_f32_e32 v76, 1.0, v77
	v_rcp_f32_e32 v76, v76
	v_add_f32_e32 v77, 1.0, v80
	v_mul_f32_e32 v80, 0xbfb8aa3b, v72
	v_rcp_f32_e32 v77, v77
	v_exp_f32_e32 v80, v80
	v_mul_f32_e32 v76, v78, v76
	v_mul_f32_e32 v70, v76, v70
	v_mul_f32_e32 v76, v79, v77
	v_add_f32_e32 v77, 1.0, v80
	v_rcp_f32_e32 v77, v77
	v_mul_f32_e32 v78, 0xbfb8aa3b, v73
	v_exp_f32_e32 v78, v78
	v_mul_f32_e32 v71, v76, v71
	v_mul_f32_e32 v72, v72, v77
	v_mul_f32_e32 v72, v72, v64
	v_add_f32_e32 v64, 1.0, v78
	v_mul_f32_e32 v76, 0xbfb8aa3b, v74
	v_rcp_f32_e32 v64, v64
	v_exp_f32_e32 v76, v76
	v_mul_f32_e32 v77, 0xbfb8aa3b, v75
	v_exp_f32_e32 v77, v77
	v_mul_f32_e32 v64, v73, v64
	v_add_f32_e32 v73, 1.0, v76
	v_rcp_f32_e32 v73, v73
	v_add_f32_e32 v76, 1.0, v77
	v_rcp_f32_e32 v76, v76
	v_mul_f32_e32 v77, v64, v65
	v_mul_f32_e32 v64, v74, v73
	v_mul_f32_e32 v73, v64, v66
	v_mul_f32_e32 v64, v75, v76
	v_mul_f32_e32 v67, v64, v67
	v_cvt_pk_bf16_f32 v64, v68, v69
	v_cvt_pk_bf16_f32 v65, v70, v71
	v_mul_f32_e32 v70, 0xbfb8aa3b, v60
	v_exp_f32_e32 v70, v70
	v_mul_f32_e32 v71, 0xbfb8aa3b, v61
	v_or_b32_e32 v68, 48, v150
	v_exp_f32_e32 v71, v71
	v_mad_i64_i32 v[68:69], s[0:1], v68, s43, v[112:113]
	v_lshl_add_u64 v[68:69], v[68:69], 0, v[114:115]
	v_cvt_pk_bf16_f32 v66, v72, v77
	v_cvt_pk_bf16_f32 v67, v73, v67
	global_store_dwordx4 v[68:69], v[64:67], off nt
	s_nop 1
	v_add_f32_e32 v64, 1.0, v70
	v_rcp_f32_e32 v64, v64
	v_add_f32_e32 v65, 1.0, v71
	v_rcp_f32_e32 v65, v65
	v_add_u32_e32 v66, 0x80, v150
	v_mul_f32_e32 v60, v60, v64
	v_mul_f32_e32 v52, v60, v52
	v_mul_f32_e32 v60, v61, v65
	v_mul_f32_e32 v61, 0xbfb8aa3b, v62
	v_exp_f32_e32 v61, v61
	v_mul_f32_e32 v64, 0xbfb8aa3b, v63
	v_exp_f32_e32 v64, v64
	v_mul_f32_e32 v53, v60, v53
	v_add_f32_e32 v60, 1.0, v61
	v_rcp_f32_e32 v60, v60
	v_add_f32_e32 v61, 1.0, v64
	v_mul_f32_e32 v64, 0xbfb8aa3b, v56
	v_rcp_f32_e32 v61, v61
	v_exp_f32_e32 v64, v64
	v_mul_f32_e32 v60, v62, v60
	v_mul_f32_e32 v54, v60, v54
	v_mul_f32_e32 v60, v63, v61
	v_add_f32_e32 v61, 1.0, v64
	v_rcp_f32_e32 v61, v61
	v_mul_f32_e32 v62, 0xbfb8aa3b, v57
	v_exp_f32_e32 v62, v62
	v_mul_f32_e32 v55, v60, v55
	v_mul_f32_e32 v56, v56, v61
	v_mul_f32_e32 v56, v56, v48
	v_add_f32_e32 v48, 1.0, v62
	v_mul_f32_e32 v60, 0xbfb8aa3b, v58
	v_rcp_f32_e32 v48, v48
	v_exp_f32_e32 v60, v60
	v_mul_f32_e32 v61, 0xbfb8aa3b, v59
	v_exp_f32_e32 v61, v61
	v_mul_f32_e32 v48, v57, v48
	v_add_f32_e32 v57, 1.0, v60
	v_rcp_f32_e32 v57, v57
	v_add_f32_e32 v60, 1.0, v61
	v_rcp_f32_e32 v60, v60
	v_mul_f32_e32 v61, v48, v49
	v_mul_f32_e32 v48, v58, v57
	v_mul_f32_e32 v57, v48, v50
	v_mul_f32_e32 v48, v59, v60
	v_mul_f32_e32 v51, v48, v51
	v_cvt_pk_bf16_f32 v48, v52, v53
	v_cvt_pk_bf16_f32 v49, v54, v55
	v_mul_f32_e32 v54, 0xbfb8aa3b, v44
	v_exp_f32_e32 v54, v54
	v_mul_f32_e32 v55, 0xbfb8aa3b, v45
	v_exp_f32_e32 v55, v55
	v_mad_i64_i32 v[52:53], s[0:1], v66, s43, v[112:113]
	v_add_f32_e32 v54, 1.0, v54
	v_rcp_f32_e32 v54, v54
	v_add_f32_e32 v55, 1.0, v55
	v_rcp_f32_e32 v55, v55
	v_lshl_add_u64 v[52:53], v[52:53], 0, v[114:115]
	v_mul_f32_e32 v44, v44, v54
	v_mul_f32_e32 v36, v44, v36
	v_mul_f32_e32 v44, v45, v55
	v_mul_f32_e32 v45, 0xbfb8aa3b, v46
	v_cvt_pk_bf16_f32 v50, v56, v61
	v_cvt_pk_bf16_f32 v51, v57, v51
	global_store_dwordx4 v[52:53], v[48:51], off nt
	v_exp_f32_e32 v45, v45
	v_mul_f32_e32 v37, v44, v37
	v_mul_f32_e32 v48, 0xbfb8aa3b, v47
	v_exp_f32_e32 v48, v48
	v_add_f32_e32 v44, 1.0, v45
	v_rcp_f32_e32 v44, v44
	v_add_f32_e32 v45, 1.0, v48
	v_mul_f32_e32 v48, 0xbfb8aa3b, v40
	v_rcp_f32_e32 v45, v45
	v_exp_f32_e32 v48, v48
	v_mul_f32_e32 v44, v46, v44
	v_mul_f32_e32 v38, v44, v38
	v_mul_f32_e32 v44, v47, v45
	v_add_f32_e32 v45, 1.0, v48
	v_rcp_f32_e32 v45, v45
	v_mul_f32_e32 v46, 0xbfb8aa3b, v41
	v_exp_f32_e32 v46, v46
	v_mul_f32_e32 v39, v44, v39
	v_mul_f32_e32 v40, v40, v45
	v_mul_f32_e32 v40, v40, v32
	v_add_f32_e32 v32, 1.0, v46
; __device__ __forceinline__ float sigmoidf_(float x) { return __builtin_amdgcn_rcpf(1.0f + __builtin_amdgcn_exp2f(-1.4426950408889634f * x)); }
; #define PG8_BAR __builtin_amdgcn_s_barrier()
; template <class Epi, class Sched>
; __device__ __forceinline__ void gemm_phase(LAS unsigned char* lds, const Gemm g, const Sched& S, const Epi& E) {
;     ...
;         if (wr == 0) PG8_BAR;
;         E(acc, cur, wr, wc, fr, fq);
;         if (!has_next) break;
; #pragma unroll
;         for (int a = 0; a < 2; ++a)
; #pragma unroll
;             for (int b = 0; b < 2; ++b)
; #pragma unroll
;                 for (int m = 0; m < 4; ++m)
; #pragma unroll
;                     for (int n = 0; n < 2; ++n) acc[a][b][m][n] = (f32x4){0.f, 0.f, 0.f, 0.f};
;         cur = nxt; cA = nA; cB = nB; ++ui;
;         if (wr == 1) PG8_BAR;
;     __device__ __forceinline__ void operator()(const Acc& acc, const Unit& u, int wr, int wc, int fr, int fq) const {
;     ...
;             for (int m = 0; m < 4; ++m) { float o[8];
; #pragma unroll
;                 for (int n = 0; n < 2; ++n)
; #pragma unroll
;                     for (int j = 0; j < 4; ++j) { const float gg = acc[ai][0][m][n][j], uu = acc[ai][1][m][n][j]; o[4 * n + j] = gg * sigmoidf_(gg) * uu; }
;                 *(u32x4*)(HM + (size_t)(row0 + ai * HALF + m * 16) * DFF + col0) = pack8(o); }
	v_mul_f32_e32 v44, 0xbfb8aa3b, v42
	v_rcp_f32_e32 v32, v32
	v_exp_f32_e32 v44, v44
	v_mul_f32_e32 v45, 0xbfb8aa3b, v43
	v_exp_f32_e32 v45, v45
	v_mul_f32_e32 v32, v41, v32
	v_add_f32_e32 v41, 1.0, v44
	v_rcp_f32_e32 v41, v41
	v_add_f32_e32 v44, 1.0, v45
	v_rcp_f32_e32 v44, v44
	v_mul_f32_e32 v45, v32, v33
	v_mul_f32_e32 v32, v42, v41
	v_mul_f32_e32 v41, v32, v34
	v_mul_f32_e32 v32, v43, v44
	v_mul_f32_e32 v35, v32, v35
	v_cvt_pk_bf16_f32 v32, v36, v37
	v_cvt_pk_bf16_f32 v33, v38, v39
	v_mul_f32_e32 v38, 0xbfb8aa3b, v28
	v_exp_f32_e32 v38, v38
	v_mul_f32_e32 v39, 0xbfb8aa3b, v29
	v_exp_f32_e32 v39, v39
	v_add_u32_e32 v36, 0x90, v150
	v_add_f32_e32 v38, 1.0, v38
	v_rcp_f32_e32 v38, v38
	v_add_f32_e32 v39, 1.0, v39
	v_rcp_f32_e32 v39, v39
	v_mad_i64_i32 v[36:37], s[0:1], v36, s43, v[112:113]
	v_mul_f32_e32 v28, v28, v38
	v_lshl_add_u64 v[36:37], v[36:37], 0, v[114:115]
	v_mul_f32_e32 v20, v28, v20
	v_mul_f32_e32 v28, v29, v39
	v_mul_f32_e32 v29, 0xbfb8aa3b, v30
	v_cvt_pk_bf16_f32 v34, v40, v45
	v_cvt_pk_bf16_f32 v35, v41, v35
	global_store_dwordx4 v[36:37], v[32:35], off nt
	v_exp_f32_e32 v29, v29
	v_mul_f32_e32 v21, v28, v21
	v_mul_f32_e32 v32, 0xbfb8aa3b, v31
	v_exp_f32_e32 v32, v32
	v_add_f32_e32 v28, 1.0, v29
	v_rcp_f32_e32 v28, v28
	v_add_f32_e32 v29, 1.0, v32
	v_mul_f32_e32 v32, 0xbfb8aa3b, v24
	v_rcp_f32_e32 v29, v29
	v_exp_f32_e32 v32, v32
	v_mul_f32_e32 v28, v30, v28
	v_mul_f32_e32 v22, v28, v22
	v_mul_f32_e32 v28, v31, v29
	v_add_f32_e32 v29, 1.0, v32
	v_rcp_f32_e32 v29, v29
	v_mul_f32_e32 v30, 0xbfb8aa3b, v25
	v_exp_f32_e32 v30, v30
	v_mul_f32_e32 v23, v28, v23
	v_mul_f32_e32 v24, v24, v29
	v_mul_f32_e32 v24, v24, v16
	v_add_f32_e32 v16, 1.0, v30
	v_mul_f32_e32 v28, 0xbfb8aa3b, v26
	v_rcp_f32_e32 v16, v16
	v_exp_f32_e32 v28, v28
	v_mul_f32_e32 v29, 0xbfb8aa3b, v27
	v_exp_f32_e32 v29, v29
	v_mul_f32_e32 v16, v25, v16
	v_add_f32_e32 v25, 1.0, v28
	v_rcp_f32_e32 v25, v25
	v_add_f32_e32 v28, 1.0, v29
	v_rcp_f32_e32 v28, v28
	v_mul_f32_e32 v29, v16, v17
	v_mul_f32_e32 v16, v26, v25
	v_mul_f32_e32 v25, v16, v18
	v_mul_f32_e32 v16, v27, v28
	v_mul_f32_e32 v19, v16, v19
	v_cvt_pk_bf16_f32 v16, v20, v21
	v_cvt_pk_bf16_f32 v17, v22, v23
	v_mul_f32_e32 v22, 0xbfb8aa3b, v12
	v_exp_f32_e32 v22, v22
	v_mul_f32_e32 v23, 0xbfb8aa3b, v13
	v_exp_f32_e32 v23, v23
	v_add_u32_e32 v20, 0xa0, v150
	v_add_f32_e32 v22, 1.0, v22
	v_rcp_f32_e32 v22, v22
	v_add_f32_e32 v23, 1.0, v23
	v_rcp_f32_e32 v23, v23
	v_mad_i64_i32 v[20:21], s[0:1], v20, s43, v[112:113]
	v_mul_f32_e32 v12, v12, v22
	v_lshl_add_u64 v[20:21], v[20:21], 0, v[114:115]
	v_mul_f32_e32 v4, v12, v4
	v_mul_f32_e32 v12, v13, v23
	v_mul_f32_e32 v13, 0xbfb8aa3b, v14
	v_cvt_pk_bf16_f32 v18, v24, v29
	v_cvt_pk_bf16_f32 v19, v25, v19
	global_store_dwordx4 v[20:21], v[16:19], off nt
	v_exp_f32_e32 v13, v13
	v_mul_f32_e32 v5, v12, v5
	v_mul_f32_e32 v16, 0xbfb8aa3b, v15
	v_exp_f32_e32 v16, v16
	v_add_f32_e32 v12, 1.0, v13
	v_rcp_f32_e32 v12, v12
	v_add_f32_e32 v13, 1.0, v16
	v_mul_f32_e32 v16, 0xbfb8aa3b, v8
	v_rcp_f32_e32 v13, v13
	v_exp_f32_e32 v16, v16
	v_mul_f32_e32 v12, v14, v12
	v_mul_f32_e32 v6, v12, v6
	v_mul_f32_e32 v12, v15, v13
	v_add_f32_e32 v13, 1.0, v16
	v_rcp_f32_e32 v13, v13
	v_mul_f32_e32 v14, 0xbfb8aa3b, v9
	v_exp_f32_e32 v14, v14
	v_mul_f32_e32 v7, v12, v7
	v_mul_f32_e32 v8, v8, v13
	v_mul_f32_e32 v8, v8, v0
	v_add_f32_e32 v0, 1.0, v14
	v_mul_f32_e32 v12, 0xbfb8aa3b, v10
	v_rcp_f32_e32 v0, v0
	v_exp_f32_e32 v12, v12
	v_mul_f32_e32 v13, 0xbfb8aa3b, v11
	v_exp_f32_e32 v13, v13
	v_mul_f32_e32 v0, v9, v0
	v_add_f32_e32 v9, 1.0, v12
	v_rcp_f32_e32 v9, v9
	v_add_f32_e32 v12, 1.0, v13
	v_rcp_f32_e32 v12, v12
	v_mul_f32_e32 v13, v0, v1
	v_mul_f32_e32 v0, v10, v9
	v_mul_f32_e32 v9, v0, v2
	v_mul_f32_e32 v0, v11, v12
	v_mul_f32_e32 v3, v0, v3
	v_cvt_pk_bf16_f32 v0, v4, v5
	v_add_u32_e32 v4, 0xb0, v150
	v_mad_i64_i32 v[4:5], s[0:1], v4, s43, v[112:113]
	v_lshl_add_u64 v[4:5], v[4:5], 0, v[114:115]
	s_mov_b64 s[0:1], -1
	v_cvt_pk_bf16_f32 v1, v6, v7
	v_cvt_pk_bf16_f32 v2, v8, v13
	v_cvt_pk_bf16_f32 v3, v9, v3
	global_store_dwordx4 v[4:5], v[0:3], off nt
	s_cbranch_vccnz .LBB0_965
	s_andn2_b64 vcc, exec, s[6:7]
	s_cbranch_vccnz .LBB0_964
	s_barrier
	s_branch .LBB0_964
